# stack34 + redundant post-barrier s_waitcnt lgkmcnt(0) removed from the GEMM main loops (the pre-barrier drain already covers it)
# speedup vs baseline: 1.0014x; 1.0014x over previous
.Lgprio0:
.LBB0_159:
	ds_read_b128 v[150:153], v147
	ds_read_b128 v[154:157], v147 offset:1024
	ds_read_b128 v[158:161], v147 offset:2048
	ds_read_b128 v[162:165], v147 offset:3072
	ds_read_b128 v[166:169], v148
	ds_read_b128 v[170:173], v148 offset:1024
	ds_read_b128 v[174:177], v148 offset:2048
	ds_read_b128 v[178:181], v148 offset:3072
	s_add_u32 s38, s36, 0x100
	s_addc_u32 s39, s37, 0
	s_cmp_eq_u32 s59, 28
	s_cselect_b32 s43, s19, s39
	s_cselect_b32 s42, s55, s38
	s_cselect_b32 s41, s17, s58
	s_cselect_b32 s40, s56, s57
	v_lshl_add_u64 v[182:183], s[36:37], 0, v[136:137]
	s_add_i32 m0, s35, 0xc000
	s_nop 0
	global_load_lds_dwordx4 v[182:183], off
	v_lshl_add_u64 v[182:183], s[36:37], 0, v[138:139]
	s_add_i32 m0, s35, 0xe000
	s_nop 0
	global_load_lds_dwordx4 v[182:183], off
	ds_read_b128 v[182:185], v149
	ds_read_b128 v[186:189], v149 offset:1024
	ds_read_b128 v[190:193], v149 offset:2048
	ds_read_b128 v[194:197], v149 offset:3072
	ds_read_b128 v[198:201], v149 offset:4096
	ds_read_b128 v[202:205], v149 offset:5120
	ds_read_b128 v[206:209], v149 offset:6144
	ds_read_b128 v[210:213], v149 offset:7168
	s_waitcnt vmcnt(8)
	s_waitcnt lgkmcnt(0)
	s_barrier
	v_mfma_f32_16x16x32_bf16 v[124:127], v[150:153], v[182:185], v[124:127]
	v_mfma_f32_16x16x32_bf16 v[120:123], v[158:161], v[182:185], v[120:123]
	v_mfma_f32_16x16x32_bf16 v[108:111], v[150:153], v[190:193], v[108:111]
	v_mfma_f32_16x16x32_bf16 v[104:107], v[158:161], v[190:193], v[104:107]
	v_mfma_f32_16x16x32_bf16 v[92:95], v[150:153], v[198:201], v[92:95]
	v_mfma_f32_16x16x32_bf16 v[88:91], v[158:161], v[198:201], v[88:91]
	v_mfma_f32_16x16x32_bf16 v[76:79], v[150:153], v[206:209], v[76:79]
	v_mfma_f32_16x16x32_bf16 v[72:75], v[158:161], v[206:209], v[72:75]
	v_mfma_f32_16x16x32_bf16 v[124:127], v[154:157], v[186:189], v[124:127]
	v_mfma_f32_16x16x32_bf16 v[120:123], v[162:165], v[186:189], v[120:123]
	v_mfma_f32_16x16x32_bf16 v[108:111], v[154:157], v[194:197], v[108:111]
	v_mfma_f32_16x16x32_bf16 v[104:107], v[162:165], v[194:197], v[104:107]
	v_mfma_f32_16x16x32_bf16 v[92:95], v[154:157], v[202:205], v[92:95]
	v_mfma_f32_16x16x32_bf16 v[88:91], v[162:165], v[202:205], v[88:91]
	v_mfma_f32_16x16x32_bf16 v[76:79], v[154:157], v[210:213], v[76:79]
	v_mfma_f32_16x16x32_bf16 v[72:75], v[162:165], v[210:213], v[72:75]
	v_mfma_f32_16x16x32_bf16 v[116:119], v[166:169], v[182:185], v[116:119]
	v_mfma_f32_16x16x32_bf16 v[112:115], v[174:177], v[182:185], v[112:115]
	v_mfma_f32_16x16x32_bf16 v[100:103], v[166:169], v[190:193], v[100:103]
	v_mfma_f32_16x16x32_bf16 v[96:99], v[174:177], v[190:193], v[96:99]
	v_mfma_f32_16x16x32_bf16 v[84:87], v[166:169], v[198:201], v[84:87]
	v_mfma_f32_16x16x32_bf16 v[80:83], v[174:177], v[198:201], v[80:83]
	v_mfma_f32_16x16x32_bf16 v[68:71], v[166:169], v[206:209], v[68:71]
	v_mfma_f32_16x16x32_bf16 v[64:67], v[174:177], v[206:209], v[64:67]
	v_mfma_f32_16x16x32_bf16 v[116:119], v[170:173], v[186:189], v[116:119]
	v_mfma_f32_16x16x32_bf16 v[112:115], v[178:181], v[186:189], v[112:115]
	v_mfma_f32_16x16x32_bf16 v[100:103], v[170:173], v[194:197], v[100:103]
	v_mfma_f32_16x16x32_bf16 v[96:99], v[178:181], v[194:197], v[96:99]
	v_mfma_f32_16x16x32_bf16 v[84:87], v[170:173], v[202:205], v[84:87]
	v_mfma_f32_16x16x32_bf16 v[80:83], v[178:181], v[202:205], v[80:83]
	v_mfma_f32_16x16x32_bf16 v[68:71], v[170:173], v[210:213], v[68:71]
	v_mfma_f32_16x16x32_bf16 v[64:67], v[178:181], v[210:213], v[64:67]
	s_barrier
	s_add_i32 s36, s51, s11
	v_lshl_add_u64 v[214:215], s[40:41], 0, v[130:131]
	s_mov_b32 m0, s36
	v_lshl_add_u64 v[216:217], s[40:41], 0, v[134:135]
	global_load_lds_dwordx4 v[214:215], off
	s_add_i32 m0, s36, 0x2000
	s_add_u32 s36, s40, 0x80000
	s_addc_u32 s37, s41, 0
	s_add_i32 s60, s52, s11
	global_load_lds_dwordx4 v[216:217], off
	v_lshl_add_u64 v[182:183], s[36:37], 0, v[130:131]
	s_mov_b32 m0, s60
	v_lshl_add_u64 v[218:219], s[42:43], 0, v[128:129]
	global_load_lds_dwordx4 v[182:183], off
	v_lshl_add_u64 v[182:183], s[36:37], 0, v[134:135]
	s_add_i32 m0, s60, 0x2000
	v_lshl_add_u64 v[220:221], s[42:43], 0, v[132:133]
	global_load_lds_dwordx4 v[182:183], off
	s_mov_b32 m0, s35
	s_nop 0
	global_load_lds_dwordx4 v[218:219], off
	s_mov_b32 m0, s44
	s_nop 0
	global_load_lds_dwordx4 v[220:221], off
	ds_read_b128 v[182:185], v149 offset:16384
	ds_read_b128 v[186:189], v149 offset:17408
	ds_read_b128 v[190:193], v149 offset:18432
	ds_read_b128 v[194:197], v149 offset:19456
	ds_read_b128 v[198:201], v149 offset:20480
	ds_read_b128 v[202:205], v149 offset:21504
	ds_read_b128 v[206:209], v149 offset:22528
	ds_read_b128 v[210:213], v149 offset:23552
	s_waitcnt vmcnt(8)
	s_waitcnt lgkmcnt(0)
	s_barrier
	v_mfma_f32_16x16x32_bf16 v[60:63], v[150:153], v[182:185], v[60:63]
	v_mfma_f32_16x16x32_bf16 v[56:59], v[158:161], v[182:185], v[56:59]
	v_mfma_f32_16x16x32_bf16 v[44:47], v[150:153], v[190:193], v[44:47]
	v_mfma_f32_16x16x32_bf16 v[40:43], v[158:161], v[190:193], v[40:43]
	v_mfma_f32_16x16x32_bf16 v[28:31], v[150:153], v[198:201], v[28:31]
	v_mfma_f32_16x16x32_bf16 v[24:27], v[158:161], v[198:201], v[24:27]
	v_mfma_f32_16x16x32_bf16 v[12:15], v[150:153], v[206:209], v[12:15]
	v_mfma_f32_16x16x32_bf16 v[8:11], v[158:161], v[206:209], v[8:11]
	v_mfma_f32_16x16x32_bf16 v[60:63], v[154:157], v[186:189], v[60:63]
	v_mfma_f32_16x16x32_bf16 v[56:59], v[162:165], v[186:189], v[56:59]
	v_mfma_f32_16x16x32_bf16 v[44:47], v[154:157], v[194:197], v[44:47]
	v_mfma_f32_16x16x32_bf16 v[40:43], v[162:165], v[194:197], v[40:43]
	v_mfma_f32_16x16x32_bf16 v[28:31], v[154:157], v[202:205], v[28:31]
	v_mfma_f32_16x16x32_bf16 v[24:27], v[162:165], v[202:205], v[24:27]
	v_mfma_f32_16x16x32_bf16 v[12:15], v[154:157], v[210:213], v[12:15]
	v_mfma_f32_16x16x32_bf16 v[8:11], v[162:165], v[210:213], v[8:11]
	v_mfma_f32_16x16x32_bf16 v[52:55], v[166:169], v[182:185], v[52:55]
	v_mfma_f32_16x16x32_bf16 v[48:51], v[174:177], v[182:185], v[48:51]
	v_mfma_f32_16x16x32_bf16 v[36:39], v[166:169], v[190:193], v[36:39]
	v_mfma_f32_16x16x32_bf16 v[32:35], v[174:177], v[190:193], v[32:35]
	v_mfma_f32_16x16x32_bf16 v[20:23], v[166:169], v[198:201], v[20:23]
	v_mfma_f32_16x16x32_bf16 v[16:19], v[174:177], v[198:201], v[16:19]
	v_mfma_f32_16x16x32_bf16 v[4:7], v[166:169], v[206:209], v[4:7]
	v_mfma_f32_16x16x32_bf16 v[0:3], v[174:177], v[206:209], v[0:3]
	v_mfma_f32_16x16x32_bf16 v[52:55], v[170:173], v[186:189], v[52:55]
	v_mfma_f32_16x16x32_bf16 v[48:51], v[178:181], v[186:189], v[48:51]
	v_mfma_f32_16x16x32_bf16 v[36:39], v[170:173], v[194:197], v[36:39]
	v_mfma_f32_16x16x32_bf16 v[32:35], v[178:181], v[194:197], v[32:35]
	v_mfma_f32_16x16x32_bf16 v[20:23], v[170:173], v[202:205], v[20:23]
	v_mfma_f32_16x16x32_bf16 v[16:19], v[178:181], v[202:205], v[16:19]
	v_mfma_f32_16x16x32_bf16 v[4:7], v[170:173], v[210:213], v[4:7]
	v_mfma_f32_16x16x32_bf16 v[0:3], v[178:181], v[210:213], v[0:3]
	s_barrier
	s_add_i32 s60, 0, 0x18000
	s_add_i32 s61, 0, 0x1c000
	v_add_u32_e32 v162, s60, v144
	v_add_u32_e32 v178, s61, v144
	ds_read_b128 v[150:153], v162
	ds_read_b128 v[154:157], v162 offset:1024
	ds_read_b128 v[158:161], v162 offset:2048
	ds_read_b128 v[162:165], v162 offset:3072
	ds_read_b128 v[166:169], v178
	ds_read_b128 v[170:173], v178 offset:1024
	ds_read_b128 v[174:177], v178 offset:2048
	ds_read_b128 v[178:181], v178 offset:3072
	s_add_u32 s36, s42, 0x80000
	s_addc_u32 s37, s43, 0
	s_mov_b32 m0, s45
	v_lshl_add_u64 v[182:183], s[36:37], 0, v[128:129]
	global_load_lds_dwordx4 v[182:183], off
	v_lshl_add_u64 v[182:183], s[36:37], 0, v[132:133]
	s_mov_b32 m0, s46
	s_nop 0
	global_load_lds_dwordx4 v[182:183], off
	ds_read_b128 v[182:185], v149 offset:32768
	ds_read_b128 v[186:189], v149 offset:33792
	ds_read_b128 v[190:193], v149 offset:34816
	ds_read_b128 v[194:197], v149 offset:35840
	ds_read_b128 v[198:201], v149 offset:36864
	ds_read_b128 v[202:205], v149 offset:37888
	ds_read_b128 v[206:209], v149 offset:38912
	ds_read_b128 v[210:213], v149 offset:39936
	s_waitcnt vmcnt(8)
	s_waitcnt lgkmcnt(0)
	s_barrier
	v_mfma_f32_16x16x32_bf16 v[124:127], v[150:153], v[182:185], v[124:127]
	v_mfma_f32_16x16x32_bf16 v[120:123], v[158:161], v[182:185], v[120:123]
	v_mfma_f32_16x16x32_bf16 v[108:111], v[150:153], v[190:193], v[108:111]
	v_mfma_f32_16x16x32_bf16 v[104:107], v[158:161], v[190:193], v[104:107]
	v_mfma_f32_16x16x32_bf16 v[92:95], v[150:153], v[198:201], v[92:95]
	v_mfma_f32_16x16x32_bf16 v[88:91], v[158:161], v[198:201], v[88:91]
	v_mfma_f32_16x16x32_bf16 v[76:79], v[150:153], v[206:209], v[76:79]
	v_mfma_f32_16x16x32_bf16 v[72:75], v[158:161], v[206:209], v[72:75]
	v_mfma_f32_16x16x32_bf16 v[124:127], v[154:157], v[186:189], v[124:127]
	v_mfma_f32_16x16x32_bf16 v[120:123], v[162:165], v[186:189], v[120:123]
	v_mfma_f32_16x16x32_bf16 v[108:111], v[154:157], v[194:197], v[108:111]
	v_mfma_f32_16x16x32_bf16 v[104:107], v[162:165], v[194:197], v[104:107]
	v_mfma_f32_16x16x32_bf16 v[92:95], v[154:157], v[202:205], v[92:95]
	v_mfma_f32_16x16x32_bf16 v[88:91], v[162:165], v[202:205], v[88:91]
	v_mfma_f32_16x16x32_bf16 v[76:79], v[154:157], v[210:213], v[76:79]
	v_mfma_f32_16x16x32_bf16 v[72:75], v[162:165], v[210:213], v[72:75]
	v_mfma_f32_16x16x32_bf16 v[116:119], v[166:169], v[182:185], v[116:119]
	v_mfma_f32_16x16x32_bf16 v[112:115], v[174:177], v[182:185], v[112:115]
	v_mfma_f32_16x16x32_bf16 v[100:103], v[166:169], v[190:193], v[100:103]
	v_mfma_f32_16x16x32_bf16 v[96:99], v[174:177], v[190:193], v[96:99]
	v_mfma_f32_16x16x32_bf16 v[84:87], v[166:169], v[198:201], v[84:87]
	v_mfma_f32_16x16x32_bf16 v[80:83], v[174:177], v[198:201], v[80:83]
	v_mfma_f32_16x16x32_bf16 v[68:71], v[166:169], v[206:209], v[68:71]
	v_mfma_f32_16x16x32_bf16 v[64:67], v[174:177], v[206:209], v[64:67]
	v_mfma_f32_16x16x32_bf16 v[116:119], v[170:173], v[186:189], v[116:119]
	v_mfma_f32_16x16x32_bf16 v[112:115], v[178:181], v[186:189], v[112:115]
	v_mfma_f32_16x16x32_bf16 v[100:103], v[170:173], v[194:197], v[100:103]
	v_mfma_f32_16x16x32_bf16 v[96:99], v[178:181], v[194:197], v[96:99]
	v_mfma_f32_16x16x32_bf16 v[84:87], v[170:173], v[202:205], v[84:87]
	v_mfma_f32_16x16x32_bf16 v[80:83], v[178:181], v[202:205], v[80:83]
	v_mfma_f32_16x16x32_bf16 v[68:71], v[170:173], v[210:213], v[68:71]
	v_mfma_f32_16x16x32_bf16 v[64:67], v[178:181], v[210:213], v[64:67]
	s_barrier
	s_add_i32 s36, s60, s11
	v_lshl_add_u64 v[182:183], v[214:215], 0, s[14:15]
	s_mov_b32 m0, s36
	s_nop 0
	global_load_lds_dwordx4 v[182:183], off
	s_add_i32 m0, s36, 0x2000
	s_add_u32 s36, s40, 0x80080
	v_lshl_add_u64 v[182:183], v[216:217], 0, s[14:15]
	s_addc_u32 s37, s41, 0
	s_add_i32 s40, s61, s11
	global_load_lds_dwordx4 v[182:183], off
	v_lshl_add_u64 v[182:183], s[36:37], 0, v[130:131]
	s_mov_b32 m0, s40
	s_nop 0
	global_load_lds_dwordx4 v[182:183], off
	v_lshl_add_u64 v[182:183], s[36:37], 0, v[134:135]
	s_add_i32 m0, s40, 0x2000
	s_nop 0
	global_load_lds_dwordx4 v[182:183], off
	v_lshl_add_u64 v[182:183], v[218:219], 0, s[14:15]
	s_mov_b32 m0, s49
	s_nop 0
	global_load_lds_dwordx4 v[182:183], off
	v_lshl_add_u64 v[182:183], v[220:221], 0, s[14:15]
	s_mov_b32 m0, s50
	s_nop 0
	global_load_lds_dwordx4 v[182:183], off
	ds_read_b128 v[182:185], v149 offset:49152
	ds_read_b128 v[186:189], v149 offset:50176
	ds_read_b128 v[190:193], v149 offset:51200
	ds_read_b128 v[194:197], v149 offset:52224
	ds_read_b128 v[198:201], v149 offset:53248
	ds_read_b128 v[202:205], v149 offset:54272
	ds_read_b128 v[206:209], v149 offset:55296
	ds_read_b128 v[210:213], v149 offset:56320
	s_waitcnt vmcnt(8)
	s_waitcnt lgkmcnt(0)
	s_barrier
	v_mfma_f32_16x16x32_bf16 v[60:63], v[150:153], v[182:185], v[60:63]
	v_mfma_f32_16x16x32_bf16 v[56:59], v[158:161], v[182:185], v[56:59]
	v_mfma_f32_16x16x32_bf16 v[44:47], v[150:153], v[190:193], v[44:47]
	v_mfma_f32_16x16x32_bf16 v[40:43], v[158:161], v[190:193], v[40:43]
	v_mfma_f32_16x16x32_bf16 v[28:31], v[150:153], v[198:201], v[28:31]
	v_mfma_f32_16x16x32_bf16 v[24:27], v[158:161], v[198:201], v[24:27]
	v_mfma_f32_16x16x32_bf16 v[12:15], v[150:153], v[206:209], v[12:15]
	v_mfma_f32_16x16x32_bf16 v[8:11], v[158:161], v[206:209], v[8:11]
	v_mfma_f32_16x16x32_bf16 v[60:63], v[154:157], v[186:189], v[60:63]
	v_mfma_f32_16x16x32_bf16 v[56:59], v[162:165], v[186:189], v[56:59]
	v_mfma_f32_16x16x32_bf16 v[44:47], v[154:157], v[194:197], v[44:47]
	v_mfma_f32_16x16x32_bf16 v[40:43], v[162:165], v[194:197], v[40:43]
	v_mfma_f32_16x16x32_bf16 v[28:31], v[154:157], v[202:205], v[28:31]
	v_mfma_f32_16x16x32_bf16 v[24:27], v[162:165], v[202:205], v[24:27]
	v_mfma_f32_16x16x32_bf16 v[12:15], v[154:157], v[210:213], v[12:15]
	v_mfma_f32_16x16x32_bf16 v[8:11], v[162:165], v[210:213], v[8:11]
	v_mfma_f32_16x16x32_bf16 v[52:55], v[166:169], v[182:185], v[52:55]
	v_mfma_f32_16x16x32_bf16 v[48:51], v[174:177], v[182:185], v[48:51]
	v_mfma_f32_16x16x32_bf16 v[36:39], v[166:169], v[190:193], v[36:39]
	v_mfma_f32_16x16x32_bf16 v[32:35], v[174:177], v[190:193], v[32:35]
	v_mfma_f32_16x16x32_bf16 v[20:23], v[166:169], v[198:201], v[20:23]
	v_mfma_f32_16x16x32_bf16 v[16:19], v[174:177], v[198:201], v[16:19]
	v_mfma_f32_16x16x32_bf16 v[4:7], v[166:169], v[206:209], v[4:7]
	v_mfma_f32_16x16x32_bf16 v[0:3], v[174:177], v[206:209], v[0:3]
	v_mfma_f32_16x16x32_bf16 v[52:55], v[170:173], v[186:189], v[52:55]
	v_mfma_f32_16x16x32_bf16 v[48:51], v[178:181], v[186:189], v[48:51]
	v_mfma_f32_16x16x32_bf16 v[36:39], v[170:173], v[194:197], v[36:39]
	v_mfma_f32_16x16x32_bf16 v[32:35], v[178:181], v[194:197], v[32:35]
	v_mfma_f32_16x16x32_bf16 v[20:23], v[170:173], v[202:205], v[20:23]
	v_mfma_f32_16x16x32_bf16 v[16:19], v[178:181], v[202:205], v[16:19]
	v_mfma_f32_16x16x32_bf16 v[4:7], v[170:173], v[210:213], v[4:7]
	v_mfma_f32_16x16x32_bf16 v[0:3], v[178:181], v[210:213], v[0:3]
	s_barrier
	s_add_i32 s59, s59, 2
	s_add_u32 s57, s57, 0x100
	s_addc_u32 s58, s58, 0
	s_cmp_gt_u32 s59, 29
	s_mov_b64 s[36:37], s[38:39]
	s_cbranch_scc0 .LBB0_159
	s_setprio 0
	s_and_b64 vcc, exec, s[6:7]
	s_cbranch_vccz .LBB0_162
	s_barrier

.Lgprio1:
.LBB0_248:
	ds_read_b128 v[144:147], v161
	ds_read_b128 v[148:151], v161 offset:1024
	ds_read_b128 v[152:155], v161 offset:2048
	ds_read_b128 v[164:167], v161 offset:3072
	ds_read_b128 v[168:171], v162
	ds_read_b128 v[172:175], v162 offset:1024
	ds_read_b128 v[176:179], v162 offset:2048
	ds_read_b128 v[180:183], v162 offset:3072
	s_add_u32 s6, s8, 0x100
	s_addc_u32 s7, s9, 0
	s_cmpk_eq_i32 s65, 0x54
	s_cselect_b32 s49, s43, s7
	s_cselect_b32 s48, s42, s6
	s_cselect_b32 s47, s45, s64
	s_cselect_b32 s46, s44, s63
	v_lshl_add_u64 v[184:185], s[8:9], 0, v[136:137]
	s_add_i32 m0, s53, 0xc000
	s_nop 0
	global_load_lds_dwordx4 v[184:185], off
	v_lshl_add_u64 v[184:185], s[8:9], 0, v[138:139]
	s_add_i32 m0, s53, 0xe000
	s_nop 0
	global_load_lds_dwordx4 v[184:185], off
	ds_read_b128 v[184:187], v163
	ds_read_b128 v[188:191], v163 offset:1024
	ds_read_b128 v[192:195], v163 offset:2048
	ds_read_b128 v[196:199], v163 offset:3072
	ds_read_b128 v[200:203], v163 offset:4096
	ds_read_b128 v[204:207], v163 offset:5120
	ds_read_b128 v[208:211], v163 offset:6144
	ds_read_b128 v[212:215], v163 offset:7168
	s_waitcnt vmcnt(8)
	s_waitcnt lgkmcnt(0)
	s_barrier
	v_mfma_f32_16x16x32_bf16 v[124:127], v[144:147], v[184:187], v[124:127]
	v_mfma_f32_16x16x32_bf16 v[120:123], v[152:155], v[184:187], v[120:123]
	v_mfma_f32_16x16x32_bf16 v[108:111], v[144:147], v[192:195], v[108:111]
	v_mfma_f32_16x16x32_bf16 v[104:107], v[152:155], v[192:195], v[104:107]
	v_mfma_f32_16x16x32_bf16 v[92:95], v[144:147], v[200:203], v[92:95]
	v_mfma_f32_16x16x32_bf16 v[88:91], v[152:155], v[200:203], v[88:91]
	v_mfma_f32_16x16x32_bf16 v[76:79], v[144:147], v[208:211], v[76:79]
	v_mfma_f32_16x16x32_bf16 v[72:75], v[152:155], v[208:211], v[72:75]
	v_mfma_f32_16x16x32_bf16 v[124:127], v[148:151], v[188:191], v[124:127]
	v_mfma_f32_16x16x32_bf16 v[120:123], v[164:167], v[188:191], v[120:123]
	v_mfma_f32_16x16x32_bf16 v[108:111], v[148:151], v[196:199], v[108:111]
	v_mfma_f32_16x16x32_bf16 v[104:107], v[164:167], v[196:199], v[104:107]
	v_mfma_f32_16x16x32_bf16 v[92:95], v[148:151], v[204:207], v[92:95]
	v_mfma_f32_16x16x32_bf16 v[88:91], v[164:167], v[204:207], v[88:91]
	v_mfma_f32_16x16x32_bf16 v[76:79], v[148:151], v[212:215], v[76:79]
	v_mfma_f32_16x16x32_bf16 v[72:75], v[164:167], v[212:215], v[72:75]
	v_mfma_f32_16x16x32_bf16 v[116:119], v[168:171], v[184:187], v[116:119]
	v_mfma_f32_16x16x32_bf16 v[112:115], v[176:179], v[184:187], v[112:115]
	v_mfma_f32_16x16x32_bf16 v[100:103], v[168:171], v[192:195], v[100:103]
	v_mfma_f32_16x16x32_bf16 v[96:99], v[176:179], v[192:195], v[96:99]
	v_mfma_f32_16x16x32_bf16 v[84:87], v[168:171], v[200:203], v[84:87]
	v_mfma_f32_16x16x32_bf16 v[80:83], v[176:179], v[200:203], v[80:83]
	v_mfma_f32_16x16x32_bf16 v[68:71], v[168:171], v[208:211], v[68:71]
	v_mfma_f32_16x16x32_bf16 v[64:67], v[176:179], v[208:211], v[64:67]
	v_mfma_f32_16x16x32_bf16 v[116:119], v[172:175], v[188:191], v[116:119]
	v_mfma_f32_16x16x32_bf16 v[112:115], v[180:183], v[188:191], v[112:115]
	v_mfma_f32_16x16x32_bf16 v[100:103], v[172:175], v[196:199], v[100:103]
	v_mfma_f32_16x16x32_bf16 v[96:99], v[180:183], v[196:199], v[96:99]
	v_mfma_f32_16x16x32_bf16 v[84:87], v[172:175], v[204:207], v[84:87]
	v_mfma_f32_16x16x32_bf16 v[80:83], v[180:183], v[204:207], v[80:83]
	v_mfma_f32_16x16x32_bf16 v[68:71], v[172:175], v[212:215], v[68:71]
	v_mfma_f32_16x16x32_bf16 v[64:67], v[180:183], v[212:215], v[64:67]
	s_barrier
	s_add_i32 s8, s58, s21
	v_lshl_add_u64 v[216:217], s[46:47], 0, v[130:131]
	s_mov_b32 m0, s8
	v_lshl_add_u64 v[218:219], s[46:47], 0, v[134:135]
	global_load_lds_dwordx4 v[216:217], off
	s_add_i32 m0, s8, 0x2000
	s_add_u32 s8, s46, 0x160000
	s_addc_u32 s9, s47, 0
	s_add_i32 s66, s59, s21
	global_load_lds_dwordx4 v[218:219], off
	v_lshl_add_u64 v[184:185], s[8:9], 0, v[130:131]
	s_mov_b32 m0, s66
	v_lshl_add_u64 v[220:221], s[48:49], 0, v[128:129]
	global_load_lds_dwordx4 v[184:185], off
	v_lshl_add_u64 v[184:185], s[8:9], 0, v[134:135]
	s_add_i32 m0, s66, 0x2000
	v_lshl_add_u64 v[222:223], s[48:49], 0, v[132:133]
	global_load_lds_dwordx4 v[184:185], off
	s_mov_b32 m0, s53
	s_nop 0
	global_load_lds_dwordx4 v[220:221], off
	s_mov_b32 m0, s54
	s_nop 0
	global_load_lds_dwordx4 v[222:223], off
	ds_read_b128 v[184:187], v163 offset:16384
	ds_read_b128 v[188:191], v163 offset:17408
	ds_read_b128 v[192:195], v163 offset:18432
	ds_read_b128 v[196:199], v163 offset:19456
	ds_read_b128 v[200:203], v163 offset:20480
	ds_read_b128 v[204:207], v163 offset:21504
	ds_read_b128 v[208:211], v163 offset:22528
	ds_read_b128 v[212:215], v163 offset:23552
	s_waitcnt vmcnt(8)
	s_waitcnt lgkmcnt(0)
	s_barrier
	v_mfma_f32_16x16x32_bf16 v[60:63], v[144:147], v[184:187], v[60:63]
	v_mfma_f32_16x16x32_bf16 v[56:59], v[152:155], v[184:187], v[56:59]
	v_mfma_f32_16x16x32_bf16 v[44:47], v[144:147], v[192:195], v[44:47]
	v_mfma_f32_16x16x32_bf16 v[40:43], v[152:155], v[192:195], v[40:43]
	v_mfma_f32_16x16x32_bf16 v[28:31], v[144:147], v[200:203], v[28:31]
	v_mfma_f32_16x16x32_bf16 v[24:27], v[152:155], v[200:203], v[24:27]
	v_mfma_f32_16x16x32_bf16 v[12:15], v[144:147], v[208:211], v[12:15]
	v_mfma_f32_16x16x32_bf16 v[8:11], v[152:155], v[208:211], v[8:11]
	v_mfma_f32_16x16x32_bf16 v[60:63], v[148:151], v[188:191], v[60:63]
	v_mfma_f32_16x16x32_bf16 v[56:59], v[164:167], v[188:191], v[56:59]
	v_mfma_f32_16x16x32_bf16 v[44:47], v[148:151], v[196:199], v[44:47]
	v_mfma_f32_16x16x32_bf16 v[40:43], v[164:167], v[196:199], v[40:43]
	v_mfma_f32_16x16x32_bf16 v[28:31], v[148:151], v[204:207], v[28:31]
	v_mfma_f32_16x16x32_bf16 v[24:27], v[164:167], v[204:207], v[24:27]
	v_mfma_f32_16x16x32_bf16 v[12:15], v[148:151], v[212:215], v[12:15]
	v_mfma_f32_16x16x32_bf16 v[8:11], v[164:167], v[212:215], v[8:11]
	v_mfma_f32_16x16x32_bf16 v[52:55], v[168:171], v[184:187], v[52:55]
	v_mfma_f32_16x16x32_bf16 v[48:51], v[176:179], v[184:187], v[48:51]
	v_mfma_f32_16x16x32_bf16 v[36:39], v[168:171], v[192:195], v[36:39]
	v_mfma_f32_16x16x32_bf16 v[32:35], v[176:179], v[192:195], v[32:35]
	v_mfma_f32_16x16x32_bf16 v[20:23], v[168:171], v[200:203], v[20:23]
	v_mfma_f32_16x16x32_bf16 v[16:19], v[176:179], v[200:203], v[16:19]
	v_mfma_f32_16x16x32_bf16 v[4:7], v[168:171], v[208:211], v[4:7]
	v_mfma_f32_16x16x32_bf16 v[0:3], v[176:179], v[208:211], v[0:3]
	v_mfma_f32_16x16x32_bf16 v[52:55], v[172:175], v[188:191], v[52:55]
	v_mfma_f32_16x16x32_bf16 v[48:51], v[180:183], v[188:191], v[48:51]
	v_mfma_f32_16x16x32_bf16 v[36:39], v[172:175], v[196:199], v[36:39]
	v_mfma_f32_16x16x32_bf16 v[32:35], v[180:183], v[196:199], v[32:35]
	v_mfma_f32_16x16x32_bf16 v[20:23], v[172:175], v[204:207], v[20:23]
	v_mfma_f32_16x16x32_bf16 v[16:19], v[180:183], v[204:207], v[16:19]
	v_mfma_f32_16x16x32_bf16 v[4:7], v[172:175], v[212:215], v[4:7]
	v_mfma_f32_16x16x32_bf16 v[0:3], v[180:183], v[212:215], v[0:3]
	s_barrier
	s_add_i32 s66, 0, 0x18000
	s_add_i32 s67, 0, 0x1c000
	v_add_u32_e32 v164, s66, v156
	v_add_u32_e32 v180, s67, v156
	ds_read_b128 v[144:147], v164
	ds_read_b128 v[148:151], v164 offset:1024
	ds_read_b128 v[152:155], v164 offset:2048
	ds_read_b128 v[164:167], v164 offset:3072
	ds_read_b128 v[168:171], v180
	ds_read_b128 v[172:175], v180 offset:1024
	ds_read_b128 v[176:179], v180 offset:2048
	ds_read_b128 v[180:183], v180 offset:3072
	s_add_u32 s8, s48, 0x160000
	s_addc_u32 s9, s49, 0
	s_mov_b32 m0, s55
	v_lshl_add_u64 v[184:185], s[8:9], 0, v[128:129]
	global_load_lds_dwordx4 v[184:185], off
	v_lshl_add_u64 v[184:185], s[8:9], 0, v[132:133]
	s_mov_b32 m0, s56
	s_nop 0
	global_load_lds_dwordx4 v[184:185], off
	ds_read_b128 v[184:187], v163 offset:32768
	ds_read_b128 v[188:191], v163 offset:33792
	ds_read_b128 v[192:195], v163 offset:34816
	ds_read_b128 v[196:199], v163 offset:35840
	ds_read_b128 v[200:203], v163 offset:36864
	ds_read_b128 v[204:207], v163 offset:37888
	ds_read_b128 v[208:211], v163 offset:38912
	ds_read_b128 v[212:215], v163 offset:39936
	s_waitcnt vmcnt(8)
	s_waitcnt lgkmcnt(0)
	s_barrier
	v_mfma_f32_16x16x32_bf16 v[124:127], v[144:147], v[184:187], v[124:127]
	v_mfma_f32_16x16x32_bf16 v[120:123], v[152:155], v[184:187], v[120:123]
	v_mfma_f32_16x16x32_bf16 v[108:111], v[144:147], v[192:195], v[108:111]
	v_mfma_f32_16x16x32_bf16 v[104:107], v[152:155], v[192:195], v[104:107]
	v_mfma_f32_16x16x32_bf16 v[92:95], v[144:147], v[200:203], v[92:95]
	v_mfma_f32_16x16x32_bf16 v[88:91], v[152:155], v[200:203], v[88:91]
	v_mfma_f32_16x16x32_bf16 v[76:79], v[144:147], v[208:211], v[76:79]
	v_mfma_f32_16x16x32_bf16 v[72:75], v[152:155], v[208:211], v[72:75]
	v_mfma_f32_16x16x32_bf16 v[124:127], v[148:151], v[188:191], v[124:127]
	v_mfma_f32_16x16x32_bf16 v[120:123], v[164:167], v[188:191], v[120:123]
	v_mfma_f32_16x16x32_bf16 v[108:111], v[148:151], v[196:199], v[108:111]
	v_mfma_f32_16x16x32_bf16 v[104:107], v[164:167], v[196:199], v[104:107]
	v_mfma_f32_16x16x32_bf16 v[92:95], v[148:151], v[204:207], v[92:95]
	v_mfma_f32_16x16x32_bf16 v[88:91], v[164:167], v[204:207], v[88:91]
	v_mfma_f32_16x16x32_bf16 v[76:79], v[148:151], v[212:215], v[76:79]
	v_mfma_f32_16x16x32_bf16 v[72:75], v[164:167], v[212:215], v[72:75]
	v_mfma_f32_16x16x32_bf16 v[116:119], v[168:171], v[184:187], v[116:119]
	v_mfma_f32_16x16x32_bf16 v[112:115], v[176:179], v[184:187], v[112:115]
	v_mfma_f32_16x16x32_bf16 v[100:103], v[168:171], v[192:195], v[100:103]
	v_mfma_f32_16x16x32_bf16 v[96:99], v[176:179], v[192:195], v[96:99]
	v_mfma_f32_16x16x32_bf16 v[84:87], v[168:171], v[200:203], v[84:87]
	v_mfma_f32_16x16x32_bf16 v[80:83], v[176:179], v[200:203], v[80:83]
	v_mfma_f32_16x16x32_bf16 v[68:71], v[168:171], v[208:211], v[68:71]
	v_mfma_f32_16x16x32_bf16 v[64:67], v[176:179], v[208:211], v[64:67]
	v_mfma_f32_16x16x32_bf16 v[116:119], v[172:175], v[188:191], v[116:119]
	v_mfma_f32_16x16x32_bf16 v[112:115], v[180:183], v[188:191], v[112:115]
	v_mfma_f32_16x16x32_bf16 v[100:103], v[172:175], v[196:199], v[100:103]
	v_mfma_f32_16x16x32_bf16 v[96:99], v[180:183], v[196:199], v[96:99]
	v_mfma_f32_16x16x32_bf16 v[84:87], v[172:175], v[204:207], v[84:87]
	v_mfma_f32_16x16x32_bf16 v[80:83], v[180:183], v[204:207], v[80:83]
	v_mfma_f32_16x16x32_bf16 v[68:71], v[172:175], v[212:215], v[68:71]
	v_mfma_f32_16x16x32_bf16 v[64:67], v[180:183], v[212:215], v[64:67]
	s_barrier
	s_add_i32 s8, s66, s21
	v_lshl_add_u64 v[184:185], v[216:217], 0, s[36:37]
	s_mov_b32 m0, s8
	s_nop 0
	global_load_lds_dwordx4 v[184:185], off
	s_add_i32 m0, s8, 0x2000
	s_add_u32 s8, s46, 0x160080
	v_lshl_add_u64 v[184:185], v[218:219], 0, s[36:37]
	s_addc_u32 s9, s47, 0
	s_add_i32 s46, s67, s21
	global_load_lds_dwordx4 v[184:185], off
	v_lshl_add_u64 v[184:185], s[8:9], 0, v[130:131]
	s_mov_b32 m0, s46
	s_nop 0
	global_load_lds_dwordx4 v[184:185], off
	v_lshl_add_u64 v[184:185], s[8:9], 0, v[134:135]
	s_add_i32 m0, s46, 0x2000
	s_nop 0
	global_load_lds_dwordx4 v[184:185], off
	v_lshl_add_u64 v[184:185], v[220:221], 0, s[36:37]
	s_mov_b32 m0, s26
	s_nop 0
	global_load_lds_dwordx4 v[184:185], off
	v_lshl_add_u64 v[184:185], v[222:223], 0, s[36:37]
	s_mov_b32 m0, s27
	s_nop 0
	global_load_lds_dwordx4 v[184:185], off
	ds_read_b128 v[184:187], v163 offset:49152
	ds_read_b128 v[188:191], v163 offset:50176
	ds_read_b128 v[192:195], v163 offset:51200
	ds_read_b128 v[196:199], v163 offset:52224
	ds_read_b128 v[200:203], v163 offset:53248
	ds_read_b128 v[204:207], v163 offset:54272
	ds_read_b128 v[208:211], v163 offset:55296
	ds_read_b128 v[212:215], v163 offset:56320
	s_waitcnt vmcnt(8)
	s_waitcnt lgkmcnt(0)
	s_barrier
	v_mfma_f32_16x16x32_bf16 v[60:63], v[144:147], v[184:187], v[60:63]
	v_mfma_f32_16x16x32_bf16 v[56:59], v[152:155], v[184:187], v[56:59]
	v_mfma_f32_16x16x32_bf16 v[44:47], v[144:147], v[192:195], v[44:47]
	v_mfma_f32_16x16x32_bf16 v[40:43], v[152:155], v[192:195], v[40:43]
	v_mfma_f32_16x16x32_bf16 v[28:31], v[144:147], v[200:203], v[28:31]
	v_mfma_f32_16x16x32_bf16 v[24:27], v[152:155], v[200:203], v[24:27]
	v_mfma_f32_16x16x32_bf16 v[12:15], v[144:147], v[208:211], v[12:15]
	v_mfma_f32_16x16x32_bf16 v[8:11], v[152:155], v[208:211], v[8:11]
	v_mfma_f32_16x16x32_bf16 v[60:63], v[148:151], v[188:191], v[60:63]
	v_mfma_f32_16x16x32_bf16 v[56:59], v[164:167], v[188:191], v[56:59]
	v_mfma_f32_16x16x32_bf16 v[44:47], v[148:151], v[196:199], v[44:47]
	v_mfma_f32_16x16x32_bf16 v[40:43], v[164:167], v[196:199], v[40:43]
	v_mfma_f32_16x16x32_bf16 v[28:31], v[148:151], v[204:207], v[28:31]
	v_mfma_f32_16x16x32_bf16 v[24:27], v[164:167], v[204:207], v[24:27]
	v_mfma_f32_16x16x32_bf16 v[12:15], v[148:151], v[212:215], v[12:15]
	v_mfma_f32_16x16x32_bf16 v[8:11], v[164:167], v[212:215], v[8:11]
	v_mfma_f32_16x16x32_bf16 v[52:55], v[168:171], v[184:187], v[52:55]
	v_mfma_f32_16x16x32_bf16 v[48:51], v[176:179], v[184:187], v[48:51]
	v_mfma_f32_16x16x32_bf16 v[36:39], v[168:171], v[192:195], v[36:39]
	v_mfma_f32_16x16x32_bf16 v[32:35], v[176:179], v[192:195], v[32:35]
	v_mfma_f32_16x16x32_bf16 v[20:23], v[168:171], v[200:203], v[20:23]
	v_mfma_f32_16x16x32_bf16 v[16:19], v[176:179], v[200:203], v[16:19]
	v_mfma_f32_16x16x32_bf16 v[4:7], v[168:171], v[208:211], v[4:7]
	v_mfma_f32_16x16x32_bf16 v[0:3], v[176:179], v[208:211], v[0:3]
	v_mfma_f32_16x16x32_bf16 v[52:55], v[172:175], v[188:191], v[52:55]
	v_mfma_f32_16x16x32_bf16 v[48:51], v[180:183], v[188:191], v[48:51]
	v_mfma_f32_16x16x32_bf16 v[36:39], v[172:175], v[196:199], v[36:39]
	v_mfma_f32_16x16x32_bf16 v[32:35], v[180:183], v[196:199], v[32:35]
	v_mfma_f32_16x16x32_bf16 v[20:23], v[172:175], v[204:207], v[20:23]
	v_mfma_f32_16x16x32_bf16 v[16:19], v[180:183], v[204:207], v[16:19]
	v_mfma_f32_16x16x32_bf16 v[4:7], v[172:175], v[212:215], v[4:7]
	v_mfma_f32_16x16x32_bf16 v[0:3], v[180:183], v[212:215], v[0:3]
	s_barrier
	s_add_i32 s65, s65, 2
	s_add_u32 s63, s63, 0x100
	s_addc_u32 s64, s64, 0
	s_cmpk_gt_u32 s65, 0x55
	s_mov_b64 s[8:9], s[6:7]
	s_cbranch_scc0 .LBB0_248
	s_setprio 0
	s_and_b64 vcc, exec, s[28:29]
	s_cbranch_vccz .LBB0_251
	s_barrier

.Lgprio2:
.LBB0_387:
	ds_read_b128 v[146:149], v156
	ds_read_b128 v[160:163], v156 offset:1024
	ds_read_b128 v[164:167], v156 offset:2048
	ds_read_b128 v[168:171], v156 offset:3072
	ds_read_b128 v[172:175], v157
	ds_read_b128 v[176:179], v157 offset:1024
	ds_read_b128 v[180:183], v157 offset:2048
	ds_read_b128 v[184:187], v157 offset:3072
	s_add_u32 s38, s36, 0x100
	s_addc_u32 s39, s37, 0
	s_cmp_eq_u32 s64, 28
	s_cselect_b32 s43, s29, s39
	s_cselect_b32 s42, s60, s38
	s_cselect_b32 s41, s19, s63
	s_cselect_b32 s40, s61, s62
	v_lshl_add_u64 v[150:151], s[36:37], 0, v[138:139]
	s_add_i32 m0, s46, 0xc000
	s_nop 0
	global_load_lds_dwordx4 v[150:151], off
	v_lshl_add_u64 v[150:151], s[36:37], 0, v[140:141]
	s_add_i32 m0, s46, 0xe000
	s_nop 0
	global_load_lds_dwordx4 v[150:151], off
	ds_read_b128 v[188:191], v158
	ds_read_b128 v[192:195], v158 offset:1024
	ds_read_b128 v[196:199], v158 offset:2048
	ds_read_b128 v[200:203], v158 offset:3072
	ds_read_b128 v[204:207], v158 offset:4096
	ds_read_b128 v[208:211], v158 offset:5120
	ds_read_b128 v[212:215], v158 offset:6144
	ds_read_b128 v[216:219], v158 offset:7168
	s_waitcnt vmcnt(8)
	s_waitcnt lgkmcnt(0)
	s_barrier
	v_mfma_f32_16x16x32_bf16 v[124:127], v[146:149], v[188:191], v[124:127]
	v_mfma_f32_16x16x32_bf16 v[120:123], v[164:167], v[188:191], v[120:123]
	v_mfma_f32_16x16x32_bf16 v[108:111], v[146:149], v[196:199], v[108:111]
	v_mfma_f32_16x16x32_bf16 v[104:107], v[164:167], v[196:199], v[104:107]
	v_mfma_f32_16x16x32_bf16 v[92:95], v[146:149], v[204:207], v[92:95]
	v_mfma_f32_16x16x32_bf16 v[88:91], v[164:167], v[204:207], v[88:91]
	v_mfma_f32_16x16x32_bf16 v[76:79], v[146:149], v[212:215], v[76:79]
	v_mfma_f32_16x16x32_bf16 v[72:75], v[164:167], v[212:215], v[72:75]
	v_mfma_f32_16x16x32_bf16 v[124:127], v[160:163], v[192:195], v[124:127]
	v_mfma_f32_16x16x32_bf16 v[120:123], v[168:171], v[192:195], v[120:123]
	v_mfma_f32_16x16x32_bf16 v[108:111], v[160:163], v[200:203], v[108:111]
	v_mfma_f32_16x16x32_bf16 v[104:107], v[168:171], v[200:203], v[104:107]
	v_mfma_f32_16x16x32_bf16 v[92:95], v[160:163], v[208:211], v[92:95]
	v_mfma_f32_16x16x32_bf16 v[88:91], v[168:171], v[208:211], v[88:91]
	v_mfma_f32_16x16x32_bf16 v[76:79], v[160:163], v[216:219], v[76:79]
	v_mfma_f32_16x16x32_bf16 v[72:75], v[168:171], v[216:219], v[72:75]
	v_mfma_f32_16x16x32_bf16 v[116:119], v[172:175], v[188:191], v[116:119]
	v_mfma_f32_16x16x32_bf16 v[112:115], v[180:183], v[188:191], v[112:115]
	v_mfma_f32_16x16x32_bf16 v[100:103], v[172:175], v[196:199], v[100:103]
	v_mfma_f32_16x16x32_bf16 v[96:99], v[180:183], v[196:199], v[96:99]
	v_mfma_f32_16x16x32_bf16 v[84:87], v[172:175], v[204:207], v[84:87]
	v_mfma_f32_16x16x32_bf16 v[80:83], v[180:183], v[204:207], v[80:83]
	v_mfma_f32_16x16x32_bf16 v[68:71], v[172:175], v[212:215], v[68:71]
	v_mfma_f32_16x16x32_bf16 v[64:67], v[180:183], v[212:215], v[64:67]
	v_mfma_f32_16x16x32_bf16 v[116:119], v[176:179], v[192:195], v[116:119]
	v_mfma_f32_16x16x32_bf16 v[112:115], v[184:187], v[192:195], v[112:115]
	v_mfma_f32_16x16x32_bf16 v[100:103], v[176:179], v[200:203], v[100:103]
	v_mfma_f32_16x16x32_bf16 v[96:99], v[184:187], v[200:203], v[96:99]
	v_mfma_f32_16x16x32_bf16 v[84:87], v[176:179], v[208:211], v[84:87]
	v_mfma_f32_16x16x32_bf16 v[80:83], v[184:187], v[208:211], v[80:83]
	v_mfma_f32_16x16x32_bf16 v[68:71], v[176:179], v[216:219], v[68:71]
	v_mfma_f32_16x16x32_bf16 v[64:67], v[184:187], v[216:219], v[64:67]
	s_barrier
	s_add_i32 s36, s55, s11
	v_lshl_add_u64 v[150:151], s[40:41], 0, v[130:131]
	s_mov_b32 m0, s36
	v_lshl_add_u64 v[220:221], s[40:41], 0, v[134:135]
	global_load_lds_dwordx4 v[150:151], off
	s_add_i32 m0, s36, 0x2000
	s_add_u32 s36, s40, 0x80000
	s_addc_u32 s37, s41, 0
	s_add_i32 s65, s56, s11
	global_load_lds_dwordx4 v[220:221], off
	v_lshl_add_u64 v[188:189], s[36:37], 0, v[130:131]
	s_mov_b32 m0, s65
	v_lshl_add_u64 v[222:223], s[42:43], 0, v[128:129]
	global_load_lds_dwordx4 v[188:189], off
	v_lshl_add_u64 v[188:189], s[36:37], 0, v[134:135]
	s_add_i32 m0, s65, 0x2000
	v_lshl_add_u64 v[224:225], s[42:43], 0, v[132:133]
	global_load_lds_dwordx4 v[188:189], off
	s_mov_b32 m0, s46
	s_nop 0
	global_load_lds_dwordx4 v[222:223], off
	s_mov_b32 m0, s47
	s_nop 0
	global_load_lds_dwordx4 v[224:225], off
	ds_read_b128 v[188:191], v158 offset:16384
	ds_read_b128 v[192:195], v158 offset:17408
	ds_read_b128 v[196:199], v158 offset:18432
	ds_read_b128 v[200:203], v158 offset:19456
	ds_read_b128 v[204:207], v158 offset:20480
	ds_read_b128 v[208:211], v158 offset:21504
	ds_read_b128 v[212:215], v158 offset:22528
	ds_read_b128 v[216:219], v158 offset:23552
	s_waitcnt vmcnt(8)
	s_waitcnt lgkmcnt(0)
	s_barrier
	v_mfma_f32_16x16x32_bf16 v[60:63], v[146:149], v[188:191], v[60:63]
	v_mfma_f32_16x16x32_bf16 v[56:59], v[164:167], v[188:191], v[56:59]
	v_mfma_f32_16x16x32_bf16 v[44:47], v[146:149], v[196:199], v[44:47]
	v_mfma_f32_16x16x32_bf16 v[40:43], v[164:167], v[196:199], v[40:43]
	v_mfma_f32_16x16x32_bf16 v[28:31], v[146:149], v[204:207], v[28:31]
	v_mfma_f32_16x16x32_bf16 v[24:27], v[164:167], v[204:207], v[24:27]
	v_mfma_f32_16x16x32_bf16 v[12:15], v[146:149], v[212:215], v[12:15]
	v_mfma_f32_16x16x32_bf16 v[8:11], v[164:167], v[212:215], v[8:11]
	v_mfma_f32_16x16x32_bf16 v[60:63], v[160:163], v[192:195], v[60:63]
	v_mfma_f32_16x16x32_bf16 v[56:59], v[168:171], v[192:195], v[56:59]
	v_mfma_f32_16x16x32_bf16 v[44:47], v[160:163], v[200:203], v[44:47]
	v_mfma_f32_16x16x32_bf16 v[40:43], v[168:171], v[200:203], v[40:43]
	v_mfma_f32_16x16x32_bf16 v[28:31], v[160:163], v[208:211], v[28:31]
	v_mfma_f32_16x16x32_bf16 v[24:27], v[168:171], v[208:211], v[24:27]
	v_mfma_f32_16x16x32_bf16 v[12:15], v[160:163], v[216:219], v[12:15]
	v_mfma_f32_16x16x32_bf16 v[8:11], v[168:171], v[216:219], v[8:11]
	v_mfma_f32_16x16x32_bf16 v[52:55], v[172:175], v[188:191], v[52:55]
	v_mfma_f32_16x16x32_bf16 v[48:51], v[180:183], v[188:191], v[48:51]
	v_mfma_f32_16x16x32_bf16 v[36:39], v[172:175], v[196:199], v[36:39]
	v_mfma_f32_16x16x32_bf16 v[32:35], v[180:183], v[196:199], v[32:35]
	v_mfma_f32_16x16x32_bf16 v[20:23], v[172:175], v[204:207], v[20:23]
	v_mfma_f32_16x16x32_bf16 v[16:19], v[180:183], v[204:207], v[16:19]
	v_mfma_f32_16x16x32_bf16 v[4:7], v[172:175], v[212:215], v[4:7]
	v_mfma_f32_16x16x32_bf16 v[0:3], v[180:183], v[212:215], v[0:3]
	v_mfma_f32_16x16x32_bf16 v[52:55], v[176:179], v[192:195], v[52:55]
	v_mfma_f32_16x16x32_bf16 v[48:51], v[184:187], v[192:195], v[48:51]
	v_mfma_f32_16x16x32_bf16 v[36:39], v[176:179], v[200:203], v[36:39]
	v_mfma_f32_16x16x32_bf16 v[32:35], v[184:187], v[200:203], v[32:35]
	v_mfma_f32_16x16x32_bf16 v[20:23], v[176:179], v[208:211], v[20:23]
	v_mfma_f32_16x16x32_bf16 v[16:19], v[184:187], v[208:211], v[16:19]
	v_mfma_f32_16x16x32_bf16 v[4:7], v[176:179], v[216:219], v[4:7]
	v_mfma_f32_16x16x32_bf16 v[0:3], v[184:187], v[216:219], v[0:3]
	s_barrier
	s_add_i32 s65, 0, 0x18000
	s_add_i32 s66, 0, 0x1c000
	v_add_u32_e32 v168, s65, v154
	v_add_u32_e32 v184, s66, v154
	ds_read_b128 v[146:149], v168
	ds_read_b128 v[160:163], v168 offset:1024
	ds_read_b128 v[164:167], v168 offset:2048
	ds_read_b128 v[168:171], v168 offset:3072
	ds_read_b128 v[172:175], v184
	ds_read_b128 v[176:179], v184 offset:1024
	ds_read_b128 v[180:183], v184 offset:2048
	ds_read_b128 v[184:187], v184 offset:3072
	s_add_u32 s36, s42, 0x80000
	s_addc_u32 s37, s43, 0
	s_mov_b32 m0, s48
	v_lshl_add_u64 v[188:189], s[36:37], 0, v[128:129]
	global_load_lds_dwordx4 v[188:189], off
	v_lshl_add_u64 v[188:189], s[36:37], 0, v[132:133]
	s_mov_b32 m0, s49
	s_nop 0
	global_load_lds_dwordx4 v[188:189], off
	ds_read_b128 v[188:191], v158 offset:32768
	ds_read_b128 v[192:195], v158 offset:33792
	ds_read_b128 v[196:199], v158 offset:34816
	ds_read_b128 v[200:203], v158 offset:35840
	ds_read_b128 v[204:207], v158 offset:36864
	ds_read_b128 v[208:211], v158 offset:37888
	ds_read_b128 v[212:215], v158 offset:38912
	ds_read_b128 v[216:219], v158 offset:39936
	s_waitcnt vmcnt(8)
	s_waitcnt lgkmcnt(0)
	s_barrier
	v_mfma_f32_16x16x32_bf16 v[124:127], v[146:149], v[188:191], v[124:127]
	v_mfma_f32_16x16x32_bf16 v[120:123], v[164:167], v[188:191], v[120:123]
	v_mfma_f32_16x16x32_bf16 v[108:111], v[146:149], v[196:199], v[108:111]
	v_mfma_f32_16x16x32_bf16 v[104:107], v[164:167], v[196:199], v[104:107]
	v_mfma_f32_16x16x32_bf16 v[92:95], v[146:149], v[204:207], v[92:95]
	v_mfma_f32_16x16x32_bf16 v[88:91], v[164:167], v[204:207], v[88:91]
	v_mfma_f32_16x16x32_bf16 v[76:79], v[146:149], v[212:215], v[76:79]
	v_mfma_f32_16x16x32_bf16 v[72:75], v[164:167], v[212:215], v[72:75]
	v_mfma_f32_16x16x32_bf16 v[124:127], v[160:163], v[192:195], v[124:127]
	v_mfma_f32_16x16x32_bf16 v[120:123], v[168:171], v[192:195], v[120:123]
	v_mfma_f32_16x16x32_bf16 v[108:111], v[160:163], v[200:203], v[108:111]
	v_mfma_f32_16x16x32_bf16 v[104:107], v[168:171], v[200:203], v[104:107]
	v_mfma_f32_16x16x32_bf16 v[92:95], v[160:163], v[208:211], v[92:95]
	v_mfma_f32_16x16x32_bf16 v[88:91], v[168:171], v[208:211], v[88:91]
	v_mfma_f32_16x16x32_bf16 v[76:79], v[160:163], v[216:219], v[76:79]
	v_mfma_f32_16x16x32_bf16 v[72:75], v[168:171], v[216:219], v[72:75]
	v_mfma_f32_16x16x32_bf16 v[116:119], v[172:175], v[188:191], v[116:119]
	v_mfma_f32_16x16x32_bf16 v[112:115], v[180:183], v[188:191], v[112:115]
	v_mfma_f32_16x16x32_bf16 v[100:103], v[172:175], v[196:199], v[100:103]
	v_mfma_f32_16x16x32_bf16 v[96:99], v[180:183], v[196:199], v[96:99]
	v_mfma_f32_16x16x32_bf16 v[84:87], v[172:175], v[204:207], v[84:87]
	v_mfma_f32_16x16x32_bf16 v[80:83], v[180:183], v[204:207], v[80:83]
	v_mfma_f32_16x16x32_bf16 v[68:71], v[172:175], v[212:215], v[68:71]
	v_mfma_f32_16x16x32_bf16 v[64:67], v[180:183], v[212:215], v[64:67]
	v_mfma_f32_16x16x32_bf16 v[116:119], v[176:179], v[192:195], v[116:119]
	v_mfma_f32_16x16x32_bf16 v[112:115], v[184:187], v[192:195], v[112:115]
	v_mfma_f32_16x16x32_bf16 v[100:103], v[176:179], v[200:203], v[100:103]
	v_mfma_f32_16x16x32_bf16 v[96:99], v[184:187], v[200:203], v[96:99]
	v_mfma_f32_16x16x32_bf16 v[84:87], v[176:179], v[208:211], v[84:87]
	v_mfma_f32_16x16x32_bf16 v[80:83], v[184:187], v[208:211], v[80:83]
	v_mfma_f32_16x16x32_bf16 v[68:71], v[176:179], v[216:219], v[68:71]
	v_mfma_f32_16x16x32_bf16 v[64:67], v[184:187], v[216:219], v[64:67]
	s_barrier
	s_add_i32 s36, s65, s11
	v_lshl_add_u64 v[150:151], v[150:151], 0, s[14:15]
	s_mov_b32 m0, s36
	s_nop 0
	global_load_lds_dwordx4 v[150:151], off
	s_add_i32 m0, s36, 0x2000
	s_add_u32 s36, s40, 0x80080
	v_lshl_add_u64 v[150:151], v[220:221], 0, s[14:15]
	s_addc_u32 s37, s41, 0
	s_add_i32 s40, s66, s11
	global_load_lds_dwordx4 v[150:151], off
	v_lshl_add_u64 v[150:151], s[36:37], 0, v[130:131]
	s_mov_b32 m0, s40
	s_nop 0
	global_load_lds_dwordx4 v[150:151], off
	v_lshl_add_u64 v[150:151], s[36:37], 0, v[134:135]
	s_add_i32 m0, s40, 0x2000
	s_nop 0
	global_load_lds_dwordx4 v[150:151], off
	v_lshl_add_u64 v[150:151], v[222:223], 0, s[14:15]
	s_mov_b32 m0, s53
	s_nop 0
	global_load_lds_dwordx4 v[150:151], off
	v_lshl_add_u64 v[150:151], v[224:225], 0, s[14:15]
	s_mov_b32 m0, s54
	s_nop 0
	global_load_lds_dwordx4 v[150:151], off
	ds_read_b128 v[188:191], v158 offset:49152
	ds_read_b128 v[192:195], v158 offset:50176
	ds_read_b128 v[196:199], v158 offset:51200
	ds_read_b128 v[200:203], v158 offset:52224
	ds_read_b128 v[204:207], v158 offset:53248
	ds_read_b128 v[208:211], v158 offset:54272
	ds_read_b128 v[212:215], v158 offset:55296
	ds_read_b128 v[216:219], v158 offset:56320
	s_waitcnt vmcnt(8)
	s_waitcnt lgkmcnt(0)
	s_barrier
	v_mfma_f32_16x16x32_bf16 v[60:63], v[146:149], v[188:191], v[60:63]
	v_mfma_f32_16x16x32_bf16 v[56:59], v[164:167], v[188:191], v[56:59]
	v_mfma_f32_16x16x32_bf16 v[44:47], v[146:149], v[196:199], v[44:47]
	v_mfma_f32_16x16x32_bf16 v[40:43], v[164:167], v[196:199], v[40:43]
	v_mfma_f32_16x16x32_bf16 v[28:31], v[146:149], v[204:207], v[28:31]
	v_mfma_f32_16x16x32_bf16 v[24:27], v[164:167], v[204:207], v[24:27]
	v_mfma_f32_16x16x32_bf16 v[12:15], v[146:149], v[212:215], v[12:15]
	v_mfma_f32_16x16x32_bf16 v[8:11], v[164:167], v[212:215], v[8:11]
	v_mfma_f32_16x16x32_bf16 v[60:63], v[160:163], v[192:195], v[60:63]
	v_mfma_f32_16x16x32_bf16 v[56:59], v[168:171], v[192:195], v[56:59]
	v_mfma_f32_16x16x32_bf16 v[44:47], v[160:163], v[200:203], v[44:47]
	v_mfma_f32_16x16x32_bf16 v[40:43], v[168:171], v[200:203], v[40:43]
	v_mfma_f32_16x16x32_bf16 v[28:31], v[160:163], v[208:211], v[28:31]
	v_mfma_f32_16x16x32_bf16 v[24:27], v[168:171], v[208:211], v[24:27]
	v_mfma_f32_16x16x32_bf16 v[12:15], v[160:163], v[216:219], v[12:15]
	v_mfma_f32_16x16x32_bf16 v[8:11], v[168:171], v[216:219], v[8:11]
	v_mfma_f32_16x16x32_bf16 v[52:55], v[172:175], v[188:191], v[52:55]
	v_mfma_f32_16x16x32_bf16 v[48:51], v[180:183], v[188:191], v[48:51]
	v_mfma_f32_16x16x32_bf16 v[36:39], v[172:175], v[196:199], v[36:39]
	v_mfma_f32_16x16x32_bf16 v[32:35], v[180:183], v[196:199], v[32:35]
	v_mfma_f32_16x16x32_bf16 v[20:23], v[172:175], v[204:207], v[20:23]
	v_mfma_f32_16x16x32_bf16 v[16:19], v[180:183], v[204:207], v[16:19]
	v_mfma_f32_16x16x32_bf16 v[4:7], v[172:175], v[212:215], v[4:7]
	v_mfma_f32_16x16x32_bf16 v[0:3], v[180:183], v[212:215], v[0:3]
	v_mfma_f32_16x16x32_bf16 v[52:55], v[176:179], v[192:195], v[52:55]
	v_mfma_f32_16x16x32_bf16 v[48:51], v[184:187], v[192:195], v[48:51]
	v_mfma_f32_16x16x32_bf16 v[36:39], v[176:179], v[200:203], v[36:39]
	v_mfma_f32_16x16x32_bf16 v[32:35], v[184:187], v[200:203], v[32:35]
	v_mfma_f32_16x16x32_bf16 v[20:23], v[176:179], v[208:211], v[20:23]
	v_mfma_f32_16x16x32_bf16 v[16:19], v[184:187], v[208:211], v[16:19]
	v_mfma_f32_16x16x32_bf16 v[4:7], v[176:179], v[216:219], v[4:7]
	v_mfma_f32_16x16x32_bf16 v[0:3], v[184:187], v[216:219], v[0:3]
	s_barrier
	s_add_i32 s64, s64, 2
	s_add_u32 s62, s62, 0x100
	s_addc_u32 s63, s63, 0
	s_cmp_gt_u32 s64, 29
	s_mov_b64 s[36:37], s[38:39]
	s_cbranch_scc0 .LBB0_387
	s_setprio 0
	s_and_b64 vcc, exec, s[4:5]
	s_cbranch_vccnz .LBB0_392
	s_cmp_gt_i32 s59, 11
	s_mov_b64 s[36:37], -1
	s_cbranch_scc1 .LBB0_393

.Lgprio3:
.LBB0_1117:
	ds_read_b128 v[144:147], v159
	ds_read_b128 v[148:151], v159 offset:1024
	ds_read_b128 v[162:165], v159 offset:2048
	ds_read_b128 v[166:169], v159 offset:3072
	ds_read_b128 v[170:173], v160
	ds_read_b128 v[174:177], v160 offset:1024
	ds_read_b128 v[178:181], v160 offset:2048
	ds_read_b128 v[182:185], v160 offset:3072
	s_add_u32 s48, s46, 0xfff80080
	s_addc_u32 s49, s47, -1
	s_cmp_eq_u32 s63, 28
	s_cselect_b32 s51, s7, s49
	s_cselect_b32 s50, s11, s48
	s_cselect_b32 s49, s37, s62
	s_cselect_b32 s48, s39, s45
	v_lshl_add_u64 v[152:153], s[46:47], 0, v[136:137]
	s_add_i32 m0, s55, 0xc000
	s_nop 0
	global_load_lds_dwordx4 v[152:153], off
	v_lshl_add_u64 v[152:153], s[46:47], 0, v[138:139]
	s_add_i32 m0, s55, 0xe000
	s_nop 0
	global_load_lds_dwordx4 v[152:153], off
	ds_read_b128 v[186:189], v161
	ds_read_b128 v[190:193], v161 offset:1024
	ds_read_b128 v[194:197], v161 offset:2048
	ds_read_b128 v[198:201], v161 offset:3072
	ds_read_b128 v[202:205], v161 offset:4096
	ds_read_b128 v[206:209], v161 offset:5120
	ds_read_b128 v[210:213], v161 offset:6144
	ds_read_b128 v[214:217], v161 offset:7168
	s_waitcnt vmcnt(8)
	s_waitcnt lgkmcnt(0)
	s_barrier
	v_mfma_f32_16x16x32_bf16 v[124:127], v[144:147], v[186:189], v[124:127]
	v_mfma_f32_16x16x32_bf16 v[120:123], v[162:165], v[186:189], v[120:123]
	v_mfma_f32_16x16x32_bf16 v[108:111], v[144:147], v[194:197], v[108:111]
	v_mfma_f32_16x16x32_bf16 v[104:107], v[162:165], v[194:197], v[104:107]
	v_mfma_f32_16x16x32_bf16 v[92:95], v[144:147], v[202:205], v[92:95]
	v_mfma_f32_16x16x32_bf16 v[88:91], v[162:165], v[202:205], v[88:91]
	v_mfma_f32_16x16x32_bf16 v[76:79], v[144:147], v[210:213], v[76:79]
	v_mfma_f32_16x16x32_bf16 v[72:75], v[162:165], v[210:213], v[72:75]
	v_mfma_f32_16x16x32_bf16 v[124:127], v[148:151], v[190:193], v[124:127]
	v_mfma_f32_16x16x32_bf16 v[120:123], v[166:169], v[190:193], v[120:123]
	v_mfma_f32_16x16x32_bf16 v[108:111], v[148:151], v[198:201], v[108:111]
	v_mfma_f32_16x16x32_bf16 v[104:107], v[166:169], v[198:201], v[104:107]
	v_mfma_f32_16x16x32_bf16 v[92:95], v[148:151], v[206:209], v[92:95]
	v_mfma_f32_16x16x32_bf16 v[88:91], v[166:169], v[206:209], v[88:91]
	v_mfma_f32_16x16x32_bf16 v[76:79], v[148:151], v[214:217], v[76:79]
	v_mfma_f32_16x16x32_bf16 v[72:75], v[166:169], v[214:217], v[72:75]
	v_mfma_f32_16x16x32_bf16 v[116:119], v[170:173], v[186:189], v[116:119]
	v_mfma_f32_16x16x32_bf16 v[112:115], v[178:181], v[186:189], v[112:115]
	v_mfma_f32_16x16x32_bf16 v[100:103], v[170:173], v[194:197], v[100:103]
	v_mfma_f32_16x16x32_bf16 v[96:99], v[178:181], v[194:197], v[96:99]
	v_mfma_f32_16x16x32_bf16 v[84:87], v[170:173], v[202:205], v[84:87]
	v_mfma_f32_16x16x32_bf16 v[80:83], v[178:181], v[202:205], v[80:83]
	v_mfma_f32_16x16x32_bf16 v[68:71], v[170:173], v[210:213], v[68:71]
	v_mfma_f32_16x16x32_bf16 v[64:67], v[178:181], v[210:213], v[64:67]
	v_mfma_f32_16x16x32_bf16 v[116:119], v[174:177], v[190:193], v[116:119]
	v_mfma_f32_16x16x32_bf16 v[112:115], v[182:185], v[190:193], v[112:115]
	v_mfma_f32_16x16x32_bf16 v[100:103], v[174:177], v[198:201], v[100:103]
	v_mfma_f32_16x16x32_bf16 v[96:99], v[182:185], v[198:201], v[96:99]
	v_mfma_f32_16x16x32_bf16 v[84:87], v[174:177], v[206:209], v[84:87]
	v_mfma_f32_16x16x32_bf16 v[80:83], v[182:185], v[206:209], v[80:83]
	v_mfma_f32_16x16x32_bf16 v[68:71], v[174:177], v[214:217], v[68:71]
	v_mfma_f32_16x16x32_bf16 v[64:67], v[182:185], v[214:217], v[64:67]
	s_barrier
	s_add_i32 s64, s60, s21
	v_lshl_add_u64 v[152:153], s[48:49], 0, v[130:131]
	s_mov_b32 m0, s64
	v_lshl_add_u64 v[218:219], s[48:49], 0, v[134:135]
	global_load_lds_dwordx4 v[152:153], off
	s_add_i32 m0, s64, 0x2000
	s_add_u32 s64, s48, 0x80000
	s_addc_u32 s65, s49, 0
	s_add_i32 s66, s61, s21
	global_load_lds_dwordx4 v[218:219], off
	v_lshl_add_u64 v[186:187], s[64:65], 0, v[130:131]
	s_mov_b32 m0, s66
	v_lshl_add_u64 v[220:221], s[50:51], 0, v[128:129]
	global_load_lds_dwordx4 v[186:187], off
	v_lshl_add_u64 v[186:187], s[64:65], 0, v[134:135]
	s_add_i32 m0, s66, 0x2000
	v_lshl_add_u64 v[222:223], s[50:51], 0, v[132:133]
	global_load_lds_dwordx4 v[186:187], off
	s_mov_b32 m0, s55
	s_nop 0
	global_load_lds_dwordx4 v[220:221], off
	s_mov_b32 m0, s56
	s_nop 0
	global_load_lds_dwordx4 v[222:223], off
	ds_read_b128 v[186:189], v161 offset:16384
	ds_read_b128 v[190:193], v161 offset:17408
	ds_read_b128 v[194:197], v161 offset:18432
	ds_read_b128 v[198:201], v161 offset:19456
	ds_read_b128 v[202:205], v161 offset:20480
	ds_read_b128 v[206:209], v161 offset:21504
	ds_read_b128 v[210:213], v161 offset:22528
	ds_read_b128 v[214:217], v161 offset:23552
	s_waitcnt vmcnt(8)
	s_waitcnt lgkmcnt(0)
	s_barrier
	v_mfma_f32_16x16x32_bf16 v[60:63], v[144:147], v[186:189], v[60:63]
	v_mfma_f32_16x16x32_bf16 v[56:59], v[162:165], v[186:189], v[56:59]
	v_mfma_f32_16x16x32_bf16 v[44:47], v[144:147], v[194:197], v[44:47]
	v_mfma_f32_16x16x32_bf16 v[40:43], v[162:165], v[194:197], v[40:43]
	v_mfma_f32_16x16x32_bf16 v[28:31], v[144:147], v[202:205], v[28:31]
	v_mfma_f32_16x16x32_bf16 v[24:27], v[162:165], v[202:205], v[24:27]
	v_mfma_f32_16x16x32_bf16 v[12:15], v[144:147], v[210:213], v[12:15]
	v_mfma_f32_16x16x32_bf16 v[8:11], v[162:165], v[210:213], v[8:11]
	v_mfma_f32_16x16x32_bf16 v[60:63], v[148:151], v[190:193], v[60:63]
	v_mfma_f32_16x16x32_bf16 v[56:59], v[166:169], v[190:193], v[56:59]
	v_mfma_f32_16x16x32_bf16 v[44:47], v[148:151], v[198:201], v[44:47]
	v_mfma_f32_16x16x32_bf16 v[40:43], v[166:169], v[198:201], v[40:43]
	v_mfma_f32_16x16x32_bf16 v[28:31], v[148:151], v[206:209], v[28:31]
	v_mfma_f32_16x16x32_bf16 v[24:27], v[166:169], v[206:209], v[24:27]
	v_mfma_f32_16x16x32_bf16 v[12:15], v[148:151], v[214:217], v[12:15]
	v_mfma_f32_16x16x32_bf16 v[8:11], v[166:169], v[214:217], v[8:11]
	v_mfma_f32_16x16x32_bf16 v[52:55], v[170:173], v[186:189], v[52:55]
	v_mfma_f32_16x16x32_bf16 v[48:51], v[178:181], v[186:189], v[48:51]
	v_mfma_f32_16x16x32_bf16 v[36:39], v[170:173], v[194:197], v[36:39]
	v_mfma_f32_16x16x32_bf16 v[32:35], v[178:181], v[194:197], v[32:35]
	v_mfma_f32_16x16x32_bf16 v[20:23], v[170:173], v[202:205], v[20:23]
	v_mfma_f32_16x16x32_bf16 v[16:19], v[178:181], v[202:205], v[16:19]
	v_mfma_f32_16x16x32_bf16 v[4:7], v[170:173], v[210:213], v[4:7]
	v_mfma_f32_16x16x32_bf16 v[0:3], v[178:181], v[210:213], v[0:3]
	v_mfma_f32_16x16x32_bf16 v[52:55], v[174:177], v[190:193], v[52:55]
	v_mfma_f32_16x16x32_bf16 v[48:51], v[182:185], v[190:193], v[48:51]
	v_mfma_f32_16x16x32_bf16 v[36:39], v[174:177], v[198:201], v[36:39]
	v_mfma_f32_16x16x32_bf16 v[32:35], v[182:185], v[198:201], v[32:35]
	v_mfma_f32_16x16x32_bf16 v[20:23], v[174:177], v[206:209], v[20:23]
	v_mfma_f32_16x16x32_bf16 v[16:19], v[182:185], v[206:209], v[16:19]
	v_mfma_f32_16x16x32_bf16 v[4:7], v[174:177], v[214:217], v[4:7]
	v_mfma_f32_16x16x32_bf16 v[0:3], v[182:185], v[214:217], v[0:3]
	s_barrier
	s_add_i32 s64, 0, 0x18000
	s_add_i32 s65, 0, 0x1c000
	v_add_u32_e32 v166, s64, v154
	v_add_u32_e32 v182, s65, v154
	ds_read_b128 v[144:147], v166
	ds_read_b128 v[148:151], v166 offset:1024
	ds_read_b128 v[162:165], v166 offset:2048
	ds_read_b128 v[166:169], v166 offset:3072
	ds_read_b128 v[170:173], v182
	ds_read_b128 v[174:177], v182 offset:1024
	ds_read_b128 v[178:181], v182 offset:2048
	ds_read_b128 v[182:185], v182 offset:3072
	s_add_u32 s50, s50, 0x80000
	s_addc_u32 s51, s51, 0
	s_mov_b32 m0, s57
	v_lshl_add_u64 v[186:187], s[50:51], 0, v[128:129]
	global_load_lds_dwordx4 v[186:187], off
	v_lshl_add_u64 v[186:187], s[50:51], 0, v[132:133]
	s_mov_b32 m0, s58
	s_nop 0
	global_load_lds_dwordx4 v[186:187], off
	ds_read_b128 v[186:189], v161 offset:32768
	ds_read_b128 v[190:193], v161 offset:33792
	ds_read_b128 v[194:197], v161 offset:34816
	ds_read_b128 v[198:201], v161 offset:35840
	ds_read_b128 v[202:205], v161 offset:36864
	ds_read_b128 v[206:209], v161 offset:37888
	ds_read_b128 v[210:213], v161 offset:38912
	ds_read_b128 v[214:217], v161 offset:39936
	s_waitcnt vmcnt(8)
	s_waitcnt lgkmcnt(0)
	s_barrier
	v_mfma_f32_16x16x32_bf16 v[124:127], v[144:147], v[186:189], v[124:127]
	v_mfma_f32_16x16x32_bf16 v[120:123], v[162:165], v[186:189], v[120:123]
	v_mfma_f32_16x16x32_bf16 v[108:111], v[144:147], v[194:197], v[108:111]
	v_mfma_f32_16x16x32_bf16 v[104:107], v[162:165], v[194:197], v[104:107]
	v_mfma_f32_16x16x32_bf16 v[92:95], v[144:147], v[202:205], v[92:95]
	v_mfma_f32_16x16x32_bf16 v[88:91], v[162:165], v[202:205], v[88:91]
	v_mfma_f32_16x16x32_bf16 v[76:79], v[144:147], v[210:213], v[76:79]
	v_mfma_f32_16x16x32_bf16 v[72:75], v[162:165], v[210:213], v[72:75]
	v_mfma_f32_16x16x32_bf16 v[124:127], v[148:151], v[190:193], v[124:127]
	v_mfma_f32_16x16x32_bf16 v[120:123], v[166:169], v[190:193], v[120:123]
	v_mfma_f32_16x16x32_bf16 v[108:111], v[148:151], v[198:201], v[108:111]
	v_mfma_f32_16x16x32_bf16 v[104:107], v[166:169], v[198:201], v[104:107]
	v_mfma_f32_16x16x32_bf16 v[92:95], v[148:151], v[206:209], v[92:95]
	v_mfma_f32_16x16x32_bf16 v[88:91], v[166:169], v[206:209], v[88:91]
	v_mfma_f32_16x16x32_bf16 v[76:79], v[148:151], v[214:217], v[76:79]
	v_mfma_f32_16x16x32_bf16 v[72:75], v[166:169], v[214:217], v[72:75]
	v_mfma_f32_16x16x32_bf16 v[116:119], v[170:173], v[186:189], v[116:119]
	v_mfma_f32_16x16x32_bf16 v[112:115], v[178:181], v[186:189], v[112:115]
	v_mfma_f32_16x16x32_bf16 v[100:103], v[170:173], v[194:197], v[100:103]
	v_mfma_f32_16x16x32_bf16 v[96:99], v[178:181], v[194:197], v[96:99]
	v_mfma_f32_16x16x32_bf16 v[84:87], v[170:173], v[202:205], v[84:87]
	v_mfma_f32_16x16x32_bf16 v[80:83], v[178:181], v[202:205], v[80:83]
	v_mfma_f32_16x16x32_bf16 v[68:71], v[170:173], v[210:213], v[68:71]
	v_mfma_f32_16x16x32_bf16 v[64:67], v[178:181], v[210:213], v[64:67]
	v_mfma_f32_16x16x32_bf16 v[116:119], v[174:177], v[190:193], v[116:119]
	v_mfma_f32_16x16x32_bf16 v[112:115], v[182:185], v[190:193], v[112:115]
	v_mfma_f32_16x16x32_bf16 v[100:103], v[174:177], v[198:201], v[100:103]
	v_mfma_f32_16x16x32_bf16 v[96:99], v[182:185], v[198:201], v[96:99]
	v_mfma_f32_16x16x32_bf16 v[84:87], v[174:177], v[206:209], v[84:87]
	v_mfma_f32_16x16x32_bf16 v[80:83], v[182:185], v[206:209], v[80:83]
	v_mfma_f32_16x16x32_bf16 v[68:71], v[174:177], v[214:217], v[68:71]
	v_mfma_f32_16x16x32_bf16 v[64:67], v[182:185], v[214:217], v[64:67]
	s_barrier
	s_add_i32 s50, s64, s21
	v_lshl_add_u64 v[152:153], v[152:153], 0, s[30:31]
	s_mov_b32 m0, s50
	s_nop 0
	global_load_lds_dwordx4 v[152:153], off
	s_add_i32 m0, s50, 0x2000
	s_add_u32 s48, s48, 0x80080
	v_lshl_add_u64 v[152:153], v[218:219], 0, s[30:31]
	s_addc_u32 s49, s49, 0
	s_add_i32 s50, s65, s21
	global_load_lds_dwordx4 v[152:153], off
	v_lshl_add_u64 v[152:153], s[48:49], 0, v[130:131]
	s_mov_b32 m0, s50
	s_nop 0
	global_load_lds_dwordx4 v[152:153], off
	v_lshl_add_u64 v[152:153], s[48:49], 0, v[134:135]
	s_add_i32 m0, s50, 0x2000
	s_nop 0
	global_load_lds_dwordx4 v[152:153], off
	v_lshl_add_u64 v[152:153], v[220:221], 0, s[30:31]
	s_mov_b32 m0, s26
	s_nop 0
	global_load_lds_dwordx4 v[152:153], off
	v_lshl_add_u64 v[152:153], v[222:223], 0, s[30:31]
	s_mov_b32 m0, s27
	s_nop 0
	global_load_lds_dwordx4 v[152:153], off
	ds_read_b128 v[186:189], v161 offset:49152
	ds_read_b128 v[190:193], v161 offset:50176
	ds_read_b128 v[194:197], v161 offset:51200
	ds_read_b128 v[198:201], v161 offset:52224
	ds_read_b128 v[202:205], v161 offset:53248
	ds_read_b128 v[206:209], v161 offset:54272
	ds_read_b128 v[210:213], v161 offset:55296
	ds_read_b128 v[214:217], v161 offset:56320
	s_waitcnt vmcnt(8)
	s_waitcnt lgkmcnt(0)
	s_barrier
	v_mfma_f32_16x16x32_bf16 v[60:63], v[144:147], v[186:189], v[60:63]
	v_mfma_f32_16x16x32_bf16 v[56:59], v[162:165], v[186:189], v[56:59]
	v_mfma_f32_16x16x32_bf16 v[44:47], v[144:147], v[194:197], v[44:47]
	v_mfma_f32_16x16x32_bf16 v[40:43], v[162:165], v[194:197], v[40:43]
	v_mfma_f32_16x16x32_bf16 v[28:31], v[144:147], v[202:205], v[28:31]
	v_mfma_f32_16x16x32_bf16 v[24:27], v[162:165], v[202:205], v[24:27]
	v_mfma_f32_16x16x32_bf16 v[12:15], v[144:147], v[210:213], v[12:15]
	v_mfma_f32_16x16x32_bf16 v[8:11], v[162:165], v[210:213], v[8:11]
	v_mfma_f32_16x16x32_bf16 v[60:63], v[148:151], v[190:193], v[60:63]
	v_mfma_f32_16x16x32_bf16 v[56:59], v[166:169], v[190:193], v[56:59]
	v_mfma_f32_16x16x32_bf16 v[44:47], v[148:151], v[198:201], v[44:47]
	v_mfma_f32_16x16x32_bf16 v[40:43], v[166:169], v[198:201], v[40:43]
	v_mfma_f32_16x16x32_bf16 v[28:31], v[148:151], v[206:209], v[28:31]
	v_mfma_f32_16x16x32_bf16 v[24:27], v[166:169], v[206:209], v[24:27]
	v_mfma_f32_16x16x32_bf16 v[12:15], v[148:151], v[214:217], v[12:15]
	v_mfma_f32_16x16x32_bf16 v[8:11], v[166:169], v[214:217], v[8:11]
	v_mfma_f32_16x16x32_bf16 v[52:55], v[170:173], v[186:189], v[52:55]
	v_mfma_f32_16x16x32_bf16 v[48:51], v[178:181], v[186:189], v[48:51]
	v_mfma_f32_16x16x32_bf16 v[36:39], v[170:173], v[194:197], v[36:39]
	v_mfma_f32_16x16x32_bf16 v[32:35], v[178:181], v[194:197], v[32:35]
	v_mfma_f32_16x16x32_bf16 v[20:23], v[170:173], v[202:205], v[20:23]
	v_mfma_f32_16x16x32_bf16 v[16:19], v[178:181], v[202:205], v[16:19]
	v_mfma_f32_16x16x32_bf16 v[4:7], v[170:173], v[210:213], v[4:7]
	v_mfma_f32_16x16x32_bf16 v[0:3], v[178:181], v[210:213], v[0:3]
	v_mfma_f32_16x16x32_bf16 v[52:55], v[174:177], v[190:193], v[52:55]
	v_mfma_f32_16x16x32_bf16 v[48:51], v[182:185], v[190:193], v[48:51]
	v_mfma_f32_16x16x32_bf16 v[36:39], v[174:177], v[198:201], v[36:39]
	v_mfma_f32_16x16x32_bf16 v[32:35], v[182:185], v[198:201], v[32:35]
	v_mfma_f32_16x16x32_bf16 v[20:23], v[174:177], v[206:209], v[20:23]
	v_mfma_f32_16x16x32_bf16 v[16:19], v[182:185], v[206:209], v[16:19]
	v_mfma_f32_16x16x32_bf16 v[4:7], v[174:177], v[214:217], v[4:7]
	v_mfma_f32_16x16x32_bf16 v[0:3], v[182:185], v[214:217], v[0:3]
	s_barrier
	s_add_i32 s63, s63, 2
	s_add_u32 s46, s46, 0x100
	s_addc_u32 s47, s47, 0
	s_add_u32 s45, s45, 0x100
	s_addc_u32 s62, s62, 0
	s_cmp_gt_u32 s63, 29
	s_cbranch_scc0 .LBB0_1117
	s_setprio 0
	s_and_b64 vcc, exec, s[16:17]
	s_cbranch_vccz .LBB0_1120
	s_barrier

.Lgprio4:
.LBB0_1240:
	ds_read_b128 v[144:147], v153
	ds_read_b128 v[158:161], v153 offset:1024
	ds_read_b128 v[162:165], v153 offset:2048
	ds_read_b128 v[166:169], v153 offset:3072
	ds_read_b128 v[170:173], v154
	ds_read_b128 v[174:177], v154 offset:1024
	ds_read_b128 v[178:181], v154 offset:2048
	ds_read_b128 v[182:185], v154 offset:3072
	s_add_u32 s40, s38, 0x100
	s_addc_u32 s41, s39, 0
	s_cmp_eq_u32 s61, 28
	s_cselect_b32 s45, s29, s41
	s_cselect_b32 s44, s57, s40
	s_cselect_b32 s43, s19, s60
	s_cselect_b32 s42, s58, s59
	v_lshl_add_u64 v[148:149], s[38:39], 0, v[136:137]
	s_add_i32 m0, s37, 0xc000
	s_nop 0
	global_load_lds_dwordx4 v[148:149], off
	v_lshl_add_u64 v[148:149], s[38:39], 0, v[138:139]
	s_add_i32 m0, s37, 0xe000
	s_nop 0
	global_load_lds_dwordx4 v[148:149], off
	ds_read_b128 v[186:189], v155
	ds_read_b128 v[190:193], v155 offset:1024
	ds_read_b128 v[194:197], v155 offset:2048
	ds_read_b128 v[198:201], v155 offset:3072
	ds_read_b128 v[202:205], v155 offset:4096
	ds_read_b128 v[206:209], v155 offset:5120
	ds_read_b128 v[210:213], v155 offset:6144
	ds_read_b128 v[214:217], v155 offset:7168
	s_waitcnt vmcnt(8)
	s_waitcnt lgkmcnt(0)
	s_barrier
	v_mfma_f32_16x16x32_bf16 v[124:127], v[144:147], v[186:189], v[124:127]
	v_mfma_f32_16x16x32_bf16 v[120:123], v[162:165], v[186:189], v[120:123]
	v_mfma_f32_16x16x32_bf16 v[108:111], v[144:147], v[194:197], v[108:111]
	v_mfma_f32_16x16x32_bf16 v[104:107], v[162:165], v[194:197], v[104:107]
	v_mfma_f32_16x16x32_bf16 v[92:95], v[144:147], v[202:205], v[92:95]
	v_mfma_f32_16x16x32_bf16 v[88:91], v[162:165], v[202:205], v[88:91]
	v_mfma_f32_16x16x32_bf16 v[76:79], v[144:147], v[210:213], v[76:79]
	v_mfma_f32_16x16x32_bf16 v[72:75], v[162:165], v[210:213], v[72:75]
	v_mfma_f32_16x16x32_bf16 v[124:127], v[158:161], v[190:193], v[124:127]
	v_mfma_f32_16x16x32_bf16 v[120:123], v[166:169], v[190:193], v[120:123]
	v_mfma_f32_16x16x32_bf16 v[108:111], v[158:161], v[198:201], v[108:111]
	v_mfma_f32_16x16x32_bf16 v[104:107], v[166:169], v[198:201], v[104:107]
	v_mfma_f32_16x16x32_bf16 v[92:95], v[158:161], v[206:209], v[92:95]
	v_mfma_f32_16x16x32_bf16 v[88:91], v[166:169], v[206:209], v[88:91]
	v_mfma_f32_16x16x32_bf16 v[76:79], v[158:161], v[214:217], v[76:79]
	v_mfma_f32_16x16x32_bf16 v[72:75], v[166:169], v[214:217], v[72:75]
	v_mfma_f32_16x16x32_bf16 v[116:119], v[170:173], v[186:189], v[116:119]
	v_mfma_f32_16x16x32_bf16 v[112:115], v[178:181], v[186:189], v[112:115]
	v_mfma_f32_16x16x32_bf16 v[100:103], v[170:173], v[194:197], v[100:103]
	v_mfma_f32_16x16x32_bf16 v[96:99], v[178:181], v[194:197], v[96:99]
	v_mfma_f32_16x16x32_bf16 v[84:87], v[170:173], v[202:205], v[84:87]
	v_mfma_f32_16x16x32_bf16 v[80:83], v[178:181], v[202:205], v[80:83]
	v_mfma_f32_16x16x32_bf16 v[68:71], v[170:173], v[210:213], v[68:71]
	v_mfma_f32_16x16x32_bf16 v[64:67], v[178:181], v[210:213], v[64:67]
	v_mfma_f32_16x16x32_bf16 v[116:119], v[174:177], v[190:193], v[116:119]
	v_mfma_f32_16x16x32_bf16 v[112:115], v[182:185], v[190:193], v[112:115]
	v_mfma_f32_16x16x32_bf16 v[100:103], v[174:177], v[198:201], v[100:103]
	v_mfma_f32_16x16x32_bf16 v[96:99], v[182:185], v[198:201], v[96:99]
	v_mfma_f32_16x16x32_bf16 v[84:87], v[174:177], v[206:209], v[84:87]
	v_mfma_f32_16x16x32_bf16 v[80:83], v[182:185], v[206:209], v[80:83]
	v_mfma_f32_16x16x32_bf16 v[68:71], v[174:177], v[214:217], v[68:71]
	v_mfma_f32_16x16x32_bf16 v[64:67], v[182:185], v[214:217], v[64:67]
	s_barrier
	s_add_i32 s38, s54, s21
	v_lshl_add_u64 v[148:149], s[42:43], 0, v[132:133]
	s_mov_b32 m0, s38
	v_lshl_add_u64 v[218:219], s[42:43], 0, v[128:129]
	global_load_lds_dwordx4 v[148:149], off
	s_add_i32 m0, s38, 0x2000
	s_add_u32 s38, s42, 0x80000
	s_addc_u32 s39, s43, 0
	s_add_i32 s62, s55, s21
	global_load_lds_dwordx4 v[218:219], off
	v_lshl_add_u64 v[186:187], s[38:39], 0, v[132:133]
	s_mov_b32 m0, s62
	v_lshl_add_u64 v[220:221], s[44:45], 0, v[134:135]
	global_load_lds_dwordx4 v[186:187], off
	v_lshl_add_u64 v[186:187], s[38:39], 0, v[128:129]
	s_add_i32 m0, s62, 0x2000
	v_lshl_add_u64 v[222:223], s[44:45], 0, v[130:131]
	global_load_lds_dwordx4 v[186:187], off
	s_mov_b32 m0, s37
	s_nop 0
	global_load_lds_dwordx4 v[220:221], off
	s_mov_b32 m0, s47
	s_nop 0
	global_load_lds_dwordx4 v[222:223], off
	ds_read_b128 v[186:189], v155 offset:16384
	ds_read_b128 v[190:193], v155 offset:17408
	ds_read_b128 v[194:197], v155 offset:18432
	ds_read_b128 v[198:201], v155 offset:19456
	ds_read_b128 v[202:205], v155 offset:20480
	ds_read_b128 v[206:209], v155 offset:21504
	ds_read_b128 v[210:213], v155 offset:22528
	ds_read_b128 v[214:217], v155 offset:23552
	s_waitcnt vmcnt(8)
	s_waitcnt lgkmcnt(0)
	s_barrier
	v_mfma_f32_16x16x32_bf16 v[60:63], v[144:147], v[186:189], v[60:63]
	v_mfma_f32_16x16x32_bf16 v[56:59], v[162:165], v[186:189], v[56:59]
	v_mfma_f32_16x16x32_bf16 v[44:47], v[144:147], v[194:197], v[44:47]
	v_mfma_f32_16x16x32_bf16 v[40:43], v[162:165], v[194:197], v[40:43]
	v_mfma_f32_16x16x32_bf16 v[28:31], v[144:147], v[202:205], v[28:31]
	v_mfma_f32_16x16x32_bf16 v[24:27], v[162:165], v[202:205], v[24:27]
	v_mfma_f32_16x16x32_bf16 v[12:15], v[144:147], v[210:213], v[12:15]
	v_mfma_f32_16x16x32_bf16 v[8:11], v[162:165], v[210:213], v[8:11]
	v_mfma_f32_16x16x32_bf16 v[60:63], v[158:161], v[190:193], v[60:63]
	v_mfma_f32_16x16x32_bf16 v[56:59], v[166:169], v[190:193], v[56:59]
	v_mfma_f32_16x16x32_bf16 v[44:47], v[158:161], v[198:201], v[44:47]
	v_mfma_f32_16x16x32_bf16 v[40:43], v[166:169], v[198:201], v[40:43]
	v_mfma_f32_16x16x32_bf16 v[28:31], v[158:161], v[206:209], v[28:31]
	v_mfma_f32_16x16x32_bf16 v[24:27], v[166:169], v[206:209], v[24:27]
	v_mfma_f32_16x16x32_bf16 v[12:15], v[158:161], v[214:217], v[12:15]
	v_mfma_f32_16x16x32_bf16 v[8:11], v[166:169], v[214:217], v[8:11]
	v_mfma_f32_16x16x32_bf16 v[52:55], v[170:173], v[186:189], v[52:55]
	v_mfma_f32_16x16x32_bf16 v[48:51], v[178:181], v[186:189], v[48:51]
	v_mfma_f32_16x16x32_bf16 v[36:39], v[170:173], v[194:197], v[36:39]
	v_mfma_f32_16x16x32_bf16 v[32:35], v[178:181], v[194:197], v[32:35]
	v_mfma_f32_16x16x32_bf16 v[20:23], v[170:173], v[202:205], v[20:23]
	v_mfma_f32_16x16x32_bf16 v[16:19], v[178:181], v[202:205], v[16:19]
	v_mfma_f32_16x16x32_bf16 v[4:7], v[170:173], v[210:213], v[4:7]
	v_mfma_f32_16x16x32_bf16 v[0:3], v[178:181], v[210:213], v[0:3]
	v_mfma_f32_16x16x32_bf16 v[52:55], v[174:177], v[190:193], v[52:55]
	v_mfma_f32_16x16x32_bf16 v[48:51], v[182:185], v[190:193], v[48:51]
	v_mfma_f32_16x16x32_bf16 v[36:39], v[174:177], v[198:201], v[36:39]
	v_mfma_f32_16x16x32_bf16 v[32:35], v[182:185], v[198:201], v[32:35]
	v_mfma_f32_16x16x32_bf16 v[20:23], v[174:177], v[206:209], v[20:23]
	v_mfma_f32_16x16x32_bf16 v[16:19], v[182:185], v[206:209], v[16:19]
	v_mfma_f32_16x16x32_bf16 v[4:7], v[174:177], v[214:217], v[4:7]
	v_mfma_f32_16x16x32_bf16 v[0:3], v[182:185], v[214:217], v[0:3]
	s_barrier
	s_add_i32 s62, 0, 0x18000
	v_add_u32_e32 v157, s62, v150
	s_add_i32 s63, 0, 0x1c000
	ds_read_b128 v[144:147], v157
	ds_read_b128 v[158:161], v157 offset:1024
	ds_read_b128 v[162:165], v157 offset:2048
	ds_read_b128 v[166:169], v157 offset:3072
	v_add_u32_e32 v157, s63, v150
	ds_read_b128 v[170:173], v157
	ds_read_b128 v[174:177], v157 offset:1024
	ds_read_b128 v[178:181], v157 offset:2048
	ds_read_b128 v[182:185], v157 offset:3072
	s_add_u32 s38, s44, 0x80000
	s_addc_u32 s39, s45, 0
	s_mov_b32 m0, s48
	v_lshl_add_u64 v[186:187], s[38:39], 0, v[134:135]
	global_load_lds_dwordx4 v[186:187], off
	v_lshl_add_u64 v[186:187], s[38:39], 0, v[130:131]
	s_mov_b32 m0, s49
	s_nop 0
	global_load_lds_dwordx4 v[186:187], off
	ds_read_b128 v[186:189], v155 offset:32768
	ds_read_b128 v[190:193], v155 offset:33792
	ds_read_b128 v[194:197], v155 offset:34816
	ds_read_b128 v[198:201], v155 offset:35840
	ds_read_b128 v[202:205], v155 offset:36864
	ds_read_b128 v[206:209], v155 offset:37888
	ds_read_b128 v[210:213], v155 offset:38912
	ds_read_b128 v[214:217], v155 offset:39936
	s_waitcnt vmcnt(8)
	s_waitcnt lgkmcnt(0)
	s_barrier
	v_mfma_f32_16x16x32_bf16 v[124:127], v[144:147], v[186:189], v[124:127]
	v_mfma_f32_16x16x32_bf16 v[120:123], v[162:165], v[186:189], v[120:123]
	v_mfma_f32_16x16x32_bf16 v[108:111], v[144:147], v[194:197], v[108:111]
	v_mfma_f32_16x16x32_bf16 v[104:107], v[162:165], v[194:197], v[104:107]
	v_mfma_f32_16x16x32_bf16 v[92:95], v[144:147], v[202:205], v[92:95]
	v_mfma_f32_16x16x32_bf16 v[88:91], v[162:165], v[202:205], v[88:91]
	v_mfma_f32_16x16x32_bf16 v[76:79], v[144:147], v[210:213], v[76:79]
	v_mfma_f32_16x16x32_bf16 v[72:75], v[162:165], v[210:213], v[72:75]
	v_mfma_f32_16x16x32_bf16 v[124:127], v[158:161], v[190:193], v[124:127]
	v_mfma_f32_16x16x32_bf16 v[120:123], v[166:169], v[190:193], v[120:123]
	v_mfma_f32_16x16x32_bf16 v[108:111], v[158:161], v[198:201], v[108:111]
	v_mfma_f32_16x16x32_bf16 v[104:107], v[166:169], v[198:201], v[104:107]
	v_mfma_f32_16x16x32_bf16 v[92:95], v[158:161], v[206:209], v[92:95]
	v_mfma_f32_16x16x32_bf16 v[88:91], v[166:169], v[206:209], v[88:91]
	v_mfma_f32_16x16x32_bf16 v[76:79], v[158:161], v[214:217], v[76:79]
	v_mfma_f32_16x16x32_bf16 v[72:75], v[166:169], v[214:217], v[72:75]
	v_mfma_f32_16x16x32_bf16 v[116:119], v[170:173], v[186:189], v[116:119]
	v_mfma_f32_16x16x32_bf16 v[112:115], v[178:181], v[186:189], v[112:115]
	v_mfma_f32_16x16x32_bf16 v[100:103], v[170:173], v[194:197], v[100:103]
	v_mfma_f32_16x16x32_bf16 v[96:99], v[178:181], v[194:197], v[96:99]
	v_mfma_f32_16x16x32_bf16 v[84:87], v[170:173], v[202:205], v[84:87]
	v_mfma_f32_16x16x32_bf16 v[80:83], v[178:181], v[202:205], v[80:83]
	v_mfma_f32_16x16x32_bf16 v[68:71], v[170:173], v[210:213], v[68:71]
	v_mfma_f32_16x16x32_bf16 v[64:67], v[178:181], v[210:213], v[64:67]
	v_mfma_f32_16x16x32_bf16 v[116:119], v[174:177], v[190:193], v[116:119]
	v_mfma_f32_16x16x32_bf16 v[112:115], v[182:185], v[190:193], v[112:115]
	v_mfma_f32_16x16x32_bf16 v[100:103], v[174:177], v[198:201], v[100:103]
	v_mfma_f32_16x16x32_bf16 v[96:99], v[182:185], v[198:201], v[96:99]
	v_mfma_f32_16x16x32_bf16 v[84:87], v[174:177], v[206:209], v[84:87]
	v_mfma_f32_16x16x32_bf16 v[80:83], v[182:185], v[206:209], v[80:83]
	v_mfma_f32_16x16x32_bf16 v[68:71], v[174:177], v[214:217], v[68:71]
	v_mfma_f32_16x16x32_bf16 v[64:67], v[182:185], v[214:217], v[64:67]
	s_barrier
	s_add_i32 s38, s62, s21
	v_lshl_add_u64 v[148:149], v[148:149], 0, s[16:17]
	s_mov_b32 m0, s38
	s_nop 0
	global_load_lds_dwordx4 v[148:149], off
	s_add_i32 m0, s38, 0x2000
	s_add_u32 s38, s42, 0x80080
	v_lshl_add_u64 v[148:149], v[218:219], 0, s[16:17]
	s_addc_u32 s39, s43, 0
	s_add_i32 s42, s63, s21
	global_load_lds_dwordx4 v[148:149], off
	v_lshl_add_u64 v[148:149], s[38:39], 0, v[132:133]
	s_mov_b32 m0, s42
	s_nop 0
	global_load_lds_dwordx4 v[148:149], off
	v_lshl_add_u64 v[148:149], s[38:39], 0, v[128:129]
	s_add_i32 m0, s42, 0x2000
	s_nop 0
	global_load_lds_dwordx4 v[148:149], off
	v_lshl_add_u64 v[148:149], v[220:221], 0, s[16:17]
	s_mov_b32 m0, s51
	s_nop 0
	global_load_lds_dwordx4 v[148:149], off
	v_lshl_add_u64 v[148:149], v[222:223], 0, s[16:17]
	s_mov_b32 m0, s52
	s_nop 0
	global_load_lds_dwordx4 v[148:149], off
	ds_read_b128 v[186:189], v155 offset:49152
	ds_read_b128 v[190:193], v155 offset:50176
	ds_read_b128 v[194:197], v155 offset:51200
	ds_read_b128 v[198:201], v155 offset:52224
	ds_read_b128 v[202:205], v155 offset:53248
	ds_read_b128 v[206:209], v155 offset:54272
	ds_read_b128 v[210:213], v155 offset:55296
	ds_read_b128 v[214:217], v155 offset:56320
	s_waitcnt vmcnt(8)
	s_waitcnt lgkmcnt(0)
	s_barrier
	v_mfma_f32_16x16x32_bf16 v[60:63], v[144:147], v[186:189], v[60:63]
	v_mfma_f32_16x16x32_bf16 v[56:59], v[162:165], v[186:189], v[56:59]
	v_mfma_f32_16x16x32_bf16 v[44:47], v[144:147], v[194:197], v[44:47]
	v_mfma_f32_16x16x32_bf16 v[40:43], v[162:165], v[194:197], v[40:43]
	v_mfma_f32_16x16x32_bf16 v[28:31], v[144:147], v[202:205], v[28:31]
	v_mfma_f32_16x16x32_bf16 v[24:27], v[162:165], v[202:205], v[24:27]
	v_mfma_f32_16x16x32_bf16 v[12:15], v[144:147], v[210:213], v[12:15]
	v_mfma_f32_16x16x32_bf16 v[8:11], v[162:165], v[210:213], v[8:11]
	v_mfma_f32_16x16x32_bf16 v[60:63], v[158:161], v[190:193], v[60:63]
	v_mfma_f32_16x16x32_bf16 v[56:59], v[166:169], v[190:193], v[56:59]
	v_mfma_f32_16x16x32_bf16 v[44:47], v[158:161], v[198:201], v[44:47]
	v_mfma_f32_16x16x32_bf16 v[40:43], v[166:169], v[198:201], v[40:43]
	v_mfma_f32_16x16x32_bf16 v[28:31], v[158:161], v[206:209], v[28:31]
	v_mfma_f32_16x16x32_bf16 v[24:27], v[166:169], v[206:209], v[24:27]
	v_mfma_f32_16x16x32_bf16 v[12:15], v[158:161], v[214:217], v[12:15]
	v_mfma_f32_16x16x32_bf16 v[8:11], v[166:169], v[214:217], v[8:11]
	v_mfma_f32_16x16x32_bf16 v[52:55], v[170:173], v[186:189], v[52:55]
	v_mfma_f32_16x16x32_bf16 v[48:51], v[178:181], v[186:189], v[48:51]
	v_mfma_f32_16x16x32_bf16 v[36:39], v[170:173], v[194:197], v[36:39]
	v_mfma_f32_16x16x32_bf16 v[32:35], v[178:181], v[194:197], v[32:35]
	v_mfma_f32_16x16x32_bf16 v[20:23], v[170:173], v[202:205], v[20:23]
	v_mfma_f32_16x16x32_bf16 v[16:19], v[178:181], v[202:205], v[16:19]
	v_mfma_f32_16x16x32_bf16 v[4:7], v[170:173], v[210:213], v[4:7]
	v_mfma_f32_16x16x32_bf16 v[0:3], v[178:181], v[210:213], v[0:3]
	v_mfma_f32_16x16x32_bf16 v[52:55], v[174:177], v[190:193], v[52:55]
	v_mfma_f32_16x16x32_bf16 v[48:51], v[182:185], v[190:193], v[48:51]
	v_mfma_f32_16x16x32_bf16 v[36:39], v[174:177], v[198:201], v[36:39]
	v_mfma_f32_16x16x32_bf16 v[32:35], v[182:185], v[198:201], v[32:35]
	v_mfma_f32_16x16x32_bf16 v[20:23], v[174:177], v[206:209], v[20:23]
	v_mfma_f32_16x16x32_bf16 v[16:19], v[182:185], v[206:209], v[16:19]
	v_mfma_f32_16x16x32_bf16 v[4:7], v[174:177], v[214:217], v[4:7]
	v_mfma_f32_16x16x32_bf16 v[0:3], v[182:185], v[214:217], v[0:3]
	s_barrier
	s_add_i32 s61, s61, 2
	s_add_u32 s59, s59, 0x100
	s_addc_u32 s60, s60, 0
	s_cmp_gt_u32 s61, 29
	s_mov_b64 s[38:39], s[40:41]
	s_cbranch_scc0 .LBB0_1240
	s_setprio 0
	s_and_b64 vcc, exec, s[6:7]
	s_cbranch_vccz .LBB0_1243
	s_barrier

.Lgprio5:
.LBB0_1327:
	ds_read_b128 v[144:147], v151
	ds_read_b128 v[154:157], v151 offset:1024
	ds_read_b128 v[158:161], v151 offset:2048
	ds_read_b128 v[162:165], v151 offset:3072
	ds_read_b128 v[166:169], v152
	ds_read_b128 v[170:173], v152 offset:1024
	ds_read_b128 v[174:177], v152 offset:2048
	ds_read_b128 v[178:181], v152 offset:3072
	s_add_u32 s34, s30, 0x100
	s_addc_u32 s35, s31, 0
	s_cmpk_eq_i32 s55, 0x54
	s_cselect_b32 s39, s5, s35
	s_cselect_b32 s38, s4, s34
	s_cselect_b32 s37, s29, s54
	s_cselect_b32 s36, s28, s53
	v_lshl_add_u64 v[182:183], s[30:31], 0, v[136:137]
	s_add_i32 m0, s40, 0xc000
	s_nop 0
	global_load_lds_dwordx4 v[182:183], off
	v_lshl_add_u64 v[182:183], s[30:31], 0, v[138:139]
	s_add_i32 m0, s40, 0xe000
	s_nop 0
	global_load_lds_dwordx4 v[182:183], off
	ds_read_b128 v[182:185], v153
	ds_read_b128 v[186:189], v153 offset:1024
	ds_read_b128 v[190:193], v153 offset:2048
	ds_read_b128 v[194:197], v153 offset:3072
	ds_read_b128 v[198:201], v153 offset:4096
	ds_read_b128 v[202:205], v153 offset:5120
	ds_read_b128 v[206:209], v153 offset:6144
	ds_read_b128 v[210:213], v153 offset:7168
	s_waitcnt vmcnt(8)
	s_waitcnt lgkmcnt(0)
	s_barrier
	v_mfma_f32_16x16x32_bf16 v[124:127], v[144:147], v[182:185], v[124:127]
	v_mfma_f32_16x16x32_bf16 v[120:123], v[158:161], v[182:185], v[120:123]
	v_mfma_f32_16x16x32_bf16 v[108:111], v[144:147], v[190:193], v[108:111]
	v_mfma_f32_16x16x32_bf16 v[104:107], v[158:161], v[190:193], v[104:107]
	v_mfma_f32_16x16x32_bf16 v[92:95], v[144:147], v[198:201], v[92:95]
	v_mfma_f32_16x16x32_bf16 v[88:91], v[158:161], v[198:201], v[88:91]
	v_mfma_f32_16x16x32_bf16 v[76:79], v[144:147], v[206:209], v[76:79]
	v_mfma_f32_16x16x32_bf16 v[72:75], v[158:161], v[206:209], v[72:75]
	v_mfma_f32_16x16x32_bf16 v[124:127], v[154:157], v[186:189], v[124:127]
	v_mfma_f32_16x16x32_bf16 v[120:123], v[162:165], v[186:189], v[120:123]
	v_mfma_f32_16x16x32_bf16 v[108:111], v[154:157], v[194:197], v[108:111]
	v_mfma_f32_16x16x32_bf16 v[104:107], v[162:165], v[194:197], v[104:107]
	v_mfma_f32_16x16x32_bf16 v[92:95], v[154:157], v[202:205], v[92:95]
	v_mfma_f32_16x16x32_bf16 v[88:91], v[162:165], v[202:205], v[88:91]
	v_mfma_f32_16x16x32_bf16 v[76:79], v[154:157], v[210:213], v[76:79]
	v_mfma_f32_16x16x32_bf16 v[72:75], v[162:165], v[210:213], v[72:75]
	v_mfma_f32_16x16x32_bf16 v[116:119], v[166:169], v[182:185], v[116:119]
	v_mfma_f32_16x16x32_bf16 v[112:115], v[174:177], v[182:185], v[112:115]
	v_mfma_f32_16x16x32_bf16 v[100:103], v[166:169], v[190:193], v[100:103]
	v_mfma_f32_16x16x32_bf16 v[96:99], v[174:177], v[190:193], v[96:99]
	v_mfma_f32_16x16x32_bf16 v[84:87], v[166:169], v[198:201], v[84:87]
	v_mfma_f32_16x16x32_bf16 v[80:83], v[174:177], v[198:201], v[80:83]
	v_mfma_f32_16x16x32_bf16 v[68:71], v[166:169], v[206:209], v[68:71]
	v_mfma_f32_16x16x32_bf16 v[64:67], v[174:177], v[206:209], v[64:67]
	v_mfma_f32_16x16x32_bf16 v[116:119], v[170:173], v[186:189], v[116:119]
	v_mfma_f32_16x16x32_bf16 v[112:115], v[178:181], v[186:189], v[112:115]
	v_mfma_f32_16x16x32_bf16 v[100:103], v[170:173], v[194:197], v[100:103]
	v_mfma_f32_16x16x32_bf16 v[96:99], v[178:181], v[194:197], v[96:99]
	v_mfma_f32_16x16x32_bf16 v[84:87], v[170:173], v[202:205], v[84:87]
	v_mfma_f32_16x16x32_bf16 v[80:83], v[178:181], v[202:205], v[80:83]
	v_mfma_f32_16x16x32_bf16 v[68:71], v[170:173], v[210:213], v[68:71]
	v_mfma_f32_16x16x32_bf16 v[64:67], v[178:181], v[210:213], v[64:67]
	s_barrier
	s_add_i32 s30, s48, s23
	v_lshl_add_u64 v[214:215], s[36:37], 0, v[130:131]
	s_mov_b32 m0, s30
	v_lshl_add_u64 v[216:217], s[36:37], 0, v[134:135]
	global_load_lds_dwordx4 v[214:215], off
	s_add_i32 m0, s30, 0x2000
	s_add_u32 s30, s36, 0x160000
	s_addc_u32 s31, s37, 0
	s_add_i32 s56, s49, s23
	global_load_lds_dwordx4 v[216:217], off
	v_lshl_add_u64 v[182:183], s[30:31], 0, v[130:131]
	s_mov_b32 m0, s56
	v_lshl_add_u64 v[218:219], s[38:39], 0, v[128:129]
	global_load_lds_dwordx4 v[182:183], off
	v_lshl_add_u64 v[182:183], s[30:31], 0, v[134:135]
	s_add_i32 m0, s56, 0x2000
	v_lshl_add_u64 v[220:221], s[38:39], 0, v[132:133]
	global_load_lds_dwordx4 v[182:183], off
	s_mov_b32 m0, s40
	s_nop 0
	global_load_lds_dwordx4 v[218:219], off
	s_mov_b32 m0, s41
	s_nop 0
	global_load_lds_dwordx4 v[220:221], off
	ds_read_b128 v[182:185], v153 offset:16384
	ds_read_b128 v[186:189], v153 offset:17408
	ds_read_b128 v[190:193], v153 offset:18432
	ds_read_b128 v[194:197], v153 offset:19456
	ds_read_b128 v[198:201], v153 offset:20480
	ds_read_b128 v[202:205], v153 offset:21504
	ds_read_b128 v[206:209], v153 offset:22528
	ds_read_b128 v[210:213], v153 offset:23552
	s_waitcnt vmcnt(8)
	s_waitcnt lgkmcnt(0)
	s_barrier
	v_mfma_f32_16x16x32_bf16 v[60:63], v[144:147], v[182:185], v[60:63]
	v_mfma_f32_16x16x32_bf16 v[56:59], v[158:161], v[182:185], v[56:59]
	v_mfma_f32_16x16x32_bf16 v[44:47], v[144:147], v[190:193], v[44:47]
	v_mfma_f32_16x16x32_bf16 v[40:43], v[158:161], v[190:193], v[40:43]
	v_mfma_f32_16x16x32_bf16 v[28:31], v[144:147], v[198:201], v[28:31]
	v_mfma_f32_16x16x32_bf16 v[24:27], v[158:161], v[198:201], v[24:27]
	v_mfma_f32_16x16x32_bf16 v[12:15], v[144:147], v[206:209], v[12:15]
	v_mfma_f32_16x16x32_bf16 v[8:11], v[158:161], v[206:209], v[8:11]
	v_mfma_f32_16x16x32_bf16 v[60:63], v[154:157], v[186:189], v[60:63]
	v_mfma_f32_16x16x32_bf16 v[56:59], v[162:165], v[186:189], v[56:59]
	v_mfma_f32_16x16x32_bf16 v[44:47], v[154:157], v[194:197], v[44:47]
	v_mfma_f32_16x16x32_bf16 v[40:43], v[162:165], v[194:197], v[40:43]
	v_mfma_f32_16x16x32_bf16 v[28:31], v[154:157], v[202:205], v[28:31]
	v_mfma_f32_16x16x32_bf16 v[24:27], v[162:165], v[202:205], v[24:27]
	v_mfma_f32_16x16x32_bf16 v[12:15], v[154:157], v[210:213], v[12:15]
	v_mfma_f32_16x16x32_bf16 v[8:11], v[162:165], v[210:213], v[8:11]
	v_mfma_f32_16x16x32_bf16 v[52:55], v[166:169], v[182:185], v[52:55]
	v_mfma_f32_16x16x32_bf16 v[48:51], v[174:177], v[182:185], v[48:51]
	v_mfma_f32_16x16x32_bf16 v[36:39], v[166:169], v[190:193], v[36:39]
	v_mfma_f32_16x16x32_bf16 v[32:35], v[174:177], v[190:193], v[32:35]
	v_mfma_f32_16x16x32_bf16 v[20:23], v[166:169], v[198:201], v[20:23]
	v_mfma_f32_16x16x32_bf16 v[16:19], v[174:177], v[198:201], v[16:19]
	v_mfma_f32_16x16x32_bf16 v[4:7], v[166:169], v[206:209], v[4:7]
	v_mfma_f32_16x16x32_bf16 v[0:3], v[174:177], v[206:209], v[0:3]
	v_mfma_f32_16x16x32_bf16 v[52:55], v[170:173], v[186:189], v[52:55]
	v_mfma_f32_16x16x32_bf16 v[48:51], v[178:181], v[186:189], v[48:51]
	v_mfma_f32_16x16x32_bf16 v[36:39], v[170:173], v[194:197], v[36:39]
	v_mfma_f32_16x16x32_bf16 v[32:35], v[178:181], v[194:197], v[32:35]
	v_mfma_f32_16x16x32_bf16 v[20:23], v[170:173], v[202:205], v[20:23]
	v_mfma_f32_16x16x32_bf16 v[16:19], v[178:181], v[202:205], v[16:19]
	v_mfma_f32_16x16x32_bf16 v[4:7], v[170:173], v[210:213], v[4:7]
	v_mfma_f32_16x16x32_bf16 v[0:3], v[178:181], v[210:213], v[0:3]
	s_barrier
	s_add_i32 s56, 0, 0x18000
	s_add_i32 s57, 0, 0x1c000
	v_add_u32_e32 v162, s56, v148
	v_add_u32_e32 v178, s57, v148
	ds_read_b128 v[144:147], v162
	ds_read_b128 v[154:157], v162 offset:1024
	ds_read_b128 v[158:161], v162 offset:2048
	ds_read_b128 v[162:165], v162 offset:3072
	ds_read_b128 v[166:169], v178
	ds_read_b128 v[170:173], v178 offset:1024
	ds_read_b128 v[174:177], v178 offset:2048
	ds_read_b128 v[178:181], v178 offset:3072
	s_add_u32 s30, s38, 0x160000
	s_addc_u32 s31, s39, 0
	s_mov_b32 m0, s42
	v_lshl_add_u64 v[182:183], s[30:31], 0, v[128:129]
	global_load_lds_dwordx4 v[182:183], off
	v_lshl_add_u64 v[182:183], s[30:31], 0, v[132:133]
	s_mov_b32 m0, s43
	s_nop 0
	global_load_lds_dwordx4 v[182:183], off
	ds_read_b128 v[182:185], v153 offset:32768
	ds_read_b128 v[186:189], v153 offset:33792
	ds_read_b128 v[190:193], v153 offset:34816
	ds_read_b128 v[194:197], v153 offset:35840
	ds_read_b128 v[198:201], v153 offset:36864
	ds_read_b128 v[202:205], v153 offset:37888
	ds_read_b128 v[206:209], v153 offset:38912
	ds_read_b128 v[210:213], v153 offset:39936
	s_waitcnt vmcnt(8)
	s_waitcnt lgkmcnt(0)
	s_barrier
	v_mfma_f32_16x16x32_bf16 v[124:127], v[144:147], v[182:185], v[124:127]
	v_mfma_f32_16x16x32_bf16 v[120:123], v[158:161], v[182:185], v[120:123]
	v_mfma_f32_16x16x32_bf16 v[108:111], v[144:147], v[190:193], v[108:111]
	v_mfma_f32_16x16x32_bf16 v[104:107], v[158:161], v[190:193], v[104:107]
	v_mfma_f32_16x16x32_bf16 v[92:95], v[144:147], v[198:201], v[92:95]
	v_mfma_f32_16x16x32_bf16 v[88:91], v[158:161], v[198:201], v[88:91]
	v_mfma_f32_16x16x32_bf16 v[76:79], v[144:147], v[206:209], v[76:79]
	v_mfma_f32_16x16x32_bf16 v[72:75], v[158:161], v[206:209], v[72:75]
	v_mfma_f32_16x16x32_bf16 v[124:127], v[154:157], v[186:189], v[124:127]
	v_mfma_f32_16x16x32_bf16 v[120:123], v[162:165], v[186:189], v[120:123]
	v_mfma_f32_16x16x32_bf16 v[108:111], v[154:157], v[194:197], v[108:111]
	v_mfma_f32_16x16x32_bf16 v[104:107], v[162:165], v[194:197], v[104:107]
	v_mfma_f32_16x16x32_bf16 v[92:95], v[154:157], v[202:205], v[92:95]
	v_mfma_f32_16x16x32_bf16 v[88:91], v[162:165], v[202:205], v[88:91]
	v_mfma_f32_16x16x32_bf16 v[76:79], v[154:157], v[210:213], v[76:79]
	v_mfma_f32_16x16x32_bf16 v[72:75], v[162:165], v[210:213], v[72:75]
	v_mfma_f32_16x16x32_bf16 v[116:119], v[166:169], v[182:185], v[116:119]
	v_mfma_f32_16x16x32_bf16 v[112:115], v[174:177], v[182:185], v[112:115]
	v_mfma_f32_16x16x32_bf16 v[100:103], v[166:169], v[190:193], v[100:103]
	v_mfma_f32_16x16x32_bf16 v[96:99], v[174:177], v[190:193], v[96:99]
	v_mfma_f32_16x16x32_bf16 v[84:87], v[166:169], v[198:201], v[84:87]
	v_mfma_f32_16x16x32_bf16 v[80:83], v[174:177], v[198:201], v[80:83]
	v_mfma_f32_16x16x32_bf16 v[68:71], v[166:169], v[206:209], v[68:71]
	v_mfma_f32_16x16x32_bf16 v[64:67], v[174:177], v[206:209], v[64:67]
	v_mfma_f32_16x16x32_bf16 v[116:119], v[170:173], v[186:189], v[116:119]
	v_mfma_f32_16x16x32_bf16 v[112:115], v[178:181], v[186:189], v[112:115]
	v_mfma_f32_16x16x32_bf16 v[100:103], v[170:173], v[194:197], v[100:103]
	v_mfma_f32_16x16x32_bf16 v[96:99], v[178:181], v[194:197], v[96:99]
	v_mfma_f32_16x16x32_bf16 v[84:87], v[170:173], v[202:205], v[84:87]
	v_mfma_f32_16x16x32_bf16 v[80:83], v[178:181], v[202:205], v[80:83]
	v_mfma_f32_16x16x32_bf16 v[68:71], v[170:173], v[210:213], v[68:71]
	v_mfma_f32_16x16x32_bf16 v[64:67], v[178:181], v[210:213], v[64:67]
	s_barrier
	s_add_i32 s30, s56, s23
	v_lshl_add_u64 v[182:183], v[214:215], 0, s[16:17]
	s_mov_b32 m0, s30
	s_nop 0
	global_load_lds_dwordx4 v[182:183], off
	s_add_i32 m0, s30, 0x2000
	s_add_u32 s30, s36, 0x160080
	v_lshl_add_u64 v[182:183], v[216:217], 0, s[16:17]
	s_addc_u32 s31, s37, 0
	s_add_i32 s36, s57, s23
	global_load_lds_dwordx4 v[182:183], off
	v_lshl_add_u64 v[182:183], s[30:31], 0, v[130:131]
	s_mov_b32 m0, s36
	s_nop 0
	global_load_lds_dwordx4 v[182:183], off
	v_lshl_add_u64 v[182:183], s[30:31], 0, v[134:135]
	s_add_i32 m0, s36, 0x2000
	s_nop 0
	global_load_lds_dwordx4 v[182:183], off
	v_lshl_add_u64 v[182:183], v[218:219], 0, s[16:17]
	s_mov_b32 m0, s45
	s_nop 0
	global_load_lds_dwordx4 v[182:183], off
	v_lshl_add_u64 v[182:183], v[220:221], 0, s[16:17]
	s_mov_b32 m0, s46
	s_nop 0
	global_load_lds_dwordx4 v[182:183], off
	ds_read_b128 v[182:185], v153 offset:49152
	ds_read_b128 v[186:189], v153 offset:50176
	ds_read_b128 v[190:193], v153 offset:51200
	ds_read_b128 v[194:197], v153 offset:52224
	ds_read_b128 v[198:201], v153 offset:53248
	ds_read_b128 v[202:205], v153 offset:54272
	ds_read_b128 v[206:209], v153 offset:55296
	ds_read_b128 v[210:213], v153 offset:56320
	s_waitcnt vmcnt(8)
	s_waitcnt lgkmcnt(0)
	s_barrier
	v_mfma_f32_16x16x32_bf16 v[60:63], v[144:147], v[182:185], v[60:63]
	v_mfma_f32_16x16x32_bf16 v[56:59], v[158:161], v[182:185], v[56:59]
	v_mfma_f32_16x16x32_bf16 v[44:47], v[144:147], v[190:193], v[44:47]
	v_mfma_f32_16x16x32_bf16 v[40:43], v[158:161], v[190:193], v[40:43]
	v_mfma_f32_16x16x32_bf16 v[28:31], v[144:147], v[198:201], v[28:31]
	v_mfma_f32_16x16x32_bf16 v[24:27], v[158:161], v[198:201], v[24:27]
	v_mfma_f32_16x16x32_bf16 v[12:15], v[144:147], v[206:209], v[12:15]
	v_mfma_f32_16x16x32_bf16 v[8:11], v[158:161], v[206:209], v[8:11]
	v_mfma_f32_16x16x32_bf16 v[60:63], v[154:157], v[186:189], v[60:63]
	v_mfma_f32_16x16x32_bf16 v[56:59], v[162:165], v[186:189], v[56:59]
	v_mfma_f32_16x16x32_bf16 v[44:47], v[154:157], v[194:197], v[44:47]
	v_mfma_f32_16x16x32_bf16 v[40:43], v[162:165], v[194:197], v[40:43]
	v_mfma_f32_16x16x32_bf16 v[28:31], v[154:157], v[202:205], v[28:31]
	v_mfma_f32_16x16x32_bf16 v[24:27], v[162:165], v[202:205], v[24:27]
	v_mfma_f32_16x16x32_bf16 v[12:15], v[154:157], v[210:213], v[12:15]
	v_mfma_f32_16x16x32_bf16 v[8:11], v[162:165], v[210:213], v[8:11]
	v_mfma_f32_16x16x32_bf16 v[52:55], v[166:169], v[182:185], v[52:55]
	v_mfma_f32_16x16x32_bf16 v[48:51], v[174:177], v[182:185], v[48:51]
	v_mfma_f32_16x16x32_bf16 v[36:39], v[166:169], v[190:193], v[36:39]
	v_mfma_f32_16x16x32_bf16 v[32:35], v[174:177], v[190:193], v[32:35]
	v_mfma_f32_16x16x32_bf16 v[20:23], v[166:169], v[198:201], v[20:23]
	v_mfma_f32_16x16x32_bf16 v[16:19], v[174:177], v[198:201], v[16:19]
	v_mfma_f32_16x16x32_bf16 v[4:7], v[166:169], v[206:209], v[4:7]
	v_mfma_f32_16x16x32_bf16 v[0:3], v[174:177], v[206:209], v[0:3]
	v_mfma_f32_16x16x32_bf16 v[52:55], v[170:173], v[186:189], v[52:55]
	v_mfma_f32_16x16x32_bf16 v[48:51], v[178:181], v[186:189], v[48:51]
	v_mfma_f32_16x16x32_bf16 v[36:39], v[170:173], v[194:197], v[36:39]
	v_mfma_f32_16x16x32_bf16 v[32:35], v[178:181], v[194:197], v[32:35]
	v_mfma_f32_16x16x32_bf16 v[20:23], v[170:173], v[202:205], v[20:23]
	v_mfma_f32_16x16x32_bf16 v[16:19], v[178:181], v[202:205], v[16:19]
	v_mfma_f32_16x16x32_bf16 v[4:7], v[170:173], v[210:213], v[4:7]
	v_mfma_f32_16x16x32_bf16 v[0:3], v[178:181], v[210:213], v[0:3]
	s_barrier
	s_add_i32 s55, s55, 2
	s_add_u32 s53, s53, 0x100
	s_addc_u32 s54, s54, 0
	s_cmpk_gt_u32 s55, 0x55
	s_mov_b64 s[30:31], s[34:35]
	s_cbranch_scc0 .LBB0_1327
	s_setprio 0
	s_and_b64 vcc, exec, s[8:9]
	s_cbranch_vccz .LBB0_1330
	s_barrier
